# attention K/V staging rewritten (batched loads, DPP); march: y_off chain first, x rows handled by waves 4-7, conflict-free M layout
# speedup vs baseline: 1.0110x; 1.0110x over previous
.Lm_fwd_1:
	s_lshl_b32 s15, s7, 23
	s_lshl_b32 s96, s6, 22
	s_add_u32 s15, s15, s96
	s_lshl_b32 s96, s11, 16
	s_add_u32 s15, s15, s96
	s_add_u32 s15, s15, 0x1b000000
	s_add_u32 s38, s36, s15
	s_addc_u32 s39, s37, 0
	s_lshl_b32 s15, s8, 1
	s_add_u32 s15, s15, s5
	s_lshl_b32 s15, s15, 20
	s_lshl_b32 s96, s6, 19
	s_add_u32 s15, s15, s96
	s_lshl_b32 s96, s11, 13
	s_add_u32 s15, s15, s96
	s_add_u32 s15, s15, 0x17000000
	s_add_u32 s40, s36, s15
	s_addc_u32 s41, s37, 0
	s_lshl_b32 s15, s6, 21
	s_add_u32 s15, s15, s9
	s_lshl_b32 s96, s11, 15
	s_add_u32 s15, s15, s96
	s_add_u32 s15, s15, 0x1f000000
	s_add_u32 s42, s36, s15
	s_addc_u32 s43, s37, 0
	s_lshl_b32 s15, s6, 25
	s_lshl_b32 s96, s8, 7
	s_add_u32 s15, s15, s96
	s_lshl_b32 s96, s5, 6
	s_add_u32 s15, s15, s96
	s_lshl_b32 s96, s11, 19
	s_add_u32 s15, s15, s96
	s_lshl_b32 s96, s51, 26
	s_add_u32 s15, s15, s96
	s_add_u32 s15, s15, 0xf000000
	s_add_u32 s44, s36, s15
	s_addc_u32 s45, s37, 0
	s_lshl_b32 s4, s3, 2
	s_lshr_b32 s5, 0x2101233, s4
	s_and_b32 s5, s5, 3
	s_lshr_b32 s6, 0x2001020, s4
	s_and_b32 s6, s6, 3
	s_lshr_b32 s7, 0x1111222, s4
	s_and_b32 s52, s7, 3
	s_sub_i32 s8, 3, s5
	s_cmp_eq_u32 s52, 2
	s_cselect_b32 s97, 2, 3
	s_sub_i32 s97, s97, s6
	s_cmp_eq_u32 s51, 0
	s_cselect_b32 s13, s5, s8
	s_cselect_b32 s14, s6, s97
	s_cmp_eq_u32 s14, s13
	s_cselect_b32 s53, 1, 0
	s_add_u32 s4, s14, 1
	s_cmp_eq_u32 s4, s13
	s_cselect_b32 s54, 1, 0
	s_waitcnt lgkmcnt(0)
	v_mov_b32_e32 v1, s10
	v_mul_f32_e32 v1, 0x3fb8aa3b, v1
	v_exp_f32_e32 v1, v1
	s_nop 0
	v_xor_b32_e32 v1, 0x80000000, v1
	s_nop 0
	v_readfirstlane_b32 s62, v1
	v_and_b32_e32 v116, 31, v175
	v_bfe_u32 v117, v175, 5, 1
	v_bfe_u32 v118, v175, 2, 2
	v_and_b32_e32 v119, 3, v175
	v_bfe_u32 v120, v175, 4, 1
	v_and_b32_e32 v121, 63, v175
	v_lshlrev_b32_e32 v122, 5, v120
	v_lshl_add_u32 v122, v119, 3, v122
	v_lshl_add_u32 v123, v117, 3, v118
	v_lshrrev_b32_e32 v124, 4, v175
	v_and_b32_e32 v125, 15, v175
	v_lshlrev_b32_e32 v125, 4, v125
	v_lshl_add_u32 v164, v124, 9, v125
	v_add_u32_e32 v165, 0x4000, v164
	v_add_u32_e32 v166, 0x8000, v164
	v_add_u32_e32 v167, 0xc000, v164
	v_mad_u32_u24 v169, v124, s59, v125
	v_and_b32_e32 v126, 0xff, v175
	v_lshlrev_b32_e32 v168, 4, v126
	v_add_u32_e32 v202, 0x1000, v168
	v_lshrrev_b32_e32 v126, 2, v126
	v_lshlrev_b32_e32 v127, 4, v119
	v_mad_u32_u24 v127, v126, s60, v127
	v_add_u32_e32 v170, 0x19800, v127
	v_lshlrev_b32_e32 v127, 2, v126
	v_add_u32_e32 v171, 0x23000, v127
	v_mov_b32_e32 v172, 0x23400
	s_lshl_b32 s4, s3, 5
	v_add_u32_e32 v128, s4, v116
	v_lshlrev_b32_e32 v129, 4, v117
	v_mad_u32_u24 v173, v128, s59, v129
	v_mad_u32_u24 v130, v116, s59, v129
	v_add_u32_e32 v210, 0x1e800, v130
	v_lshlrev_b32_e32 v130, 2, v128
	v_add_u32_e32 v211, 0x23000, v130
	v_lshlrev_b32_e32 v130, 3, v117
	v_lshl_add_u32 v212, v128, 12, v130
	v_mad_u32_u24 v130, v123, s60, v122
	v_add_u32_e32 v208, 0x19800, v130
	v_add_u32_e32 v192, 0x1c000, v130
	v_mad_u32_u24 v131, v123, s59, v122
	v_lshrrev_b32_e32 v130, 3, v122
	v_lshl_add_u32 v130, v118, 3, v130
	v_lshl_add_u32 v130, v117, 2, v130
	s_lshl_b32 s4, s3, 3
	v_add_u32_e32 v130, s4, v130
	v_add_u32_e32 v127, 2, v130
	v_and_b32_e32 v130, 31, v130
	v_and_b32_e32 v127, 31, v127
	v_lshlrev_b32_e32 v126, 8, v123
	v_lshl_add_u32 v130, v130, 3, v126
	v_lshl_add_u32 v127, v127, 3, v126
	v_add_u32_e32 v209, 0x11000, v130
	v_add_u32_e32 v110, 0x11400, v127
	s_sub_i32 s4, s3, 4
	s_lshl_b32 s4, s4, 6
	v_add_u32_e32 v130, s4, v131
	v_add_u32_e32 v193, 0x8800, v130
	v_lshlrev_b32_e32 v130, 3, v117
	v_mad_u32_u24 v130, v116, s59, v130
	v_add_u32_e32 v130, s4, v130
	v_add_u32_e32 v194, 0x1e800, v130
	v_lshlrev_b32_e32 v195, 9, v121
	v_lshlrev_b32_e32 v130, 3, v121
	v_add_u32_e32 v196, 0x23000, v130
	s_lshl_b32 s4, s13, 5
	v_add_u32_e32 v130, s4, v116
	v_mad_u32_u24 v216, v130, s59, v129
	s_lshl_b32 s5, s14, 5
	v_add_u32_e32 v131, s5, v116
	v_mad_u32_u24 v217, v131, s59, v129
	s_lshl_b32 s6, s13, 7
	s_add_u32 s6, s6, 0x23000
	v_add_u32_e32 v222, s6, v129
	v_lshlrev_b32_e32 v130, 2, v131
	v_add_u32_e32 v223, 0x23000, v130
	v_and_b32_e32 v130, 3, v116
	v_lshlrev_b32_e32 v130, 3, v130
	v_bfe_u32 v126, v116, 2, 2
	v_lshl_add_u32 v130, v126, 1, v130
	v_add_u32_e32 v130, v117, v130
	s_lshl_b32 s6, s13, 3
	v_add_u32_e32 v130, s6, v130
	v_lshlrev_b32_e32 v126, 8, v131
	v_add_u32_e32 v126, 0x11000, v126
	v_add_u32_e32 v127, 0, v130
	v_and_b32_e32 v127, 31, v127
	v_lshl_add_u32 v224, v127, 3, v126
	v_add_u32_e32 v127, 2, v130
	v_and_b32_e32 v127, 31, v127
	v_lshl_add_u32 v3, v127, 3, v126
	v_add_u32_e32 v127, 4, v130
	v_and_b32_e32 v127, 31, v127
	v_lshl_add_u32 v108, v127, 3, v126
	v_add_u32_e32 v127, 6, v130
	v_and_b32_e32 v127, 31, v127
	v_lshl_add_u32 v109, v127, 3, v126
	v_lshlrev_b32_e32 v129, 2, v117
	s_cmp_eq_u32 s51, 0
	s_cbranch_scc0 .Lm_mbwd_2
	v_add_u32_e32 v130, 0, v129
	v_cmp_le_u32_e64 s[64:65], v116, v130
	v_add_u32_e32 v130, 1, v129
	v_cmp_le_u32_e64 s[66:67], v116, v130
	v_add_u32_e32 v130, 2, v129
	v_cmp_le_u32_e64 s[68:69], v116, v130
	v_add_u32_e32 v130, 3, v129
	v_cmp_le_u32_e64 s[70:71], v116, v130
	v_add_u32_e32 v130, 8, v129
	v_cmp_le_u32_e64 s[72:73], v116, v130
	v_add_u32_e32 v130, 9, v129
	v_cmp_le_u32_e64 s[74:75], v116, v130
	v_add_u32_e32 v130, 10, v129
	v_cmp_le_u32_e64 s[76:77], v116, v130
	v_add_u32_e32 v130, 11, v129
	v_cmp_le_u32_e64 s[78:79], v116, v130
	v_add_u32_e32 v130, 16, v129
	v_cmp_le_u32_e64 s[80:81], v116, v130
	v_add_u32_e32 v130, 17, v129
	v_cmp_le_u32_e64 s[82:83], v116, v130
	v_add_u32_e32 v130, 18, v129
	v_cmp_le_u32_e64 s[84:85], v116, v130
	v_add_u32_e32 v130, 19, v129
	v_cmp_le_u32_e64 s[86:87], v116, v130
	v_add_u32_e32 v130, 24, v129
	v_cmp_le_u32_e64 s[88:89], v116, v130
	v_add_u32_e32 v130, 25, v129
	v_cmp_le_u32_e64 s[90:91], v116, v130
	v_add_u32_e32 v130, 26, v129
	v_cmp_le_u32_e64 s[92:93], v116, v130
	v_add_u32_e32 v130, 27, v129
	v_cmp_le_u32_e64 s[94:95], v116, v130
	s_branch .Lm_mdone_3

.Lm_pro_w7_4:
	s_cmp_lt_u32 s3, 4
	s_cbranch_scc1 .Lm_pro_lo_6
	global_load_dwordx4 v[4:7], v164, s[38:39]
	global_load_dwordx4 v[20:23], v164, s[38:39] offset:256
	global_load_dwordx4 v[8:11], v165, s[38:39]
	global_load_dwordx4 v[24:27], v165, s[38:39] offset:256
	global_load_dwordx4 v[12:15], v166, s[38:39]
	global_load_dwordx4 v[28:31], v166, s[38:39] offset:256
	global_load_dwordx4 v[16:19], v167, s[38:39]
	global_load_dwordx4 v[32:35], v167, s[38:39] offset:256
	global_load_dwordx4 v[36:39], v168, s[40:41]
	global_load_dwordx4 v[198:201], v202, s[40:41]
	s_add_u32 s38, s38, s46
	s_addc_u32 s39, s39, s55
	s_add_u32 s40, s40, s47
	s_addc_u32 s41, s41, s55
	global_load_dwordx4 v[40:43], v164, s[38:39]
	global_load_dwordx4 v[56:59], v164, s[38:39] offset:256
	global_load_dwordx4 v[44:47], v165, s[38:39]
	global_load_dwordx4 v[60:63], v165, s[38:39] offset:256
	global_load_dwordx4 v[48:51], v166, s[38:39]
	global_load_dwordx4 v[64:67], v166, s[38:39] offset:256
	global_load_dwordx4 v[52:55], v167, s[38:39]
	global_load_dwordx4 v[68:71], v167, s[38:39] offset:256
	global_load_dwordx4 v[72:75], v168, s[40:41]
	global_load_dwordx4 v[208:211], v202, s[40:41]
	s_add_u32 s38, s38, s46
	s_addc_u32 s39, s39, s55
	s_add_u32 s40, s40, s47
	s_addc_u32 s41, s41, s55
	s_branch .Lm_pro_lj_7
.Lm_pro_lo_6:
	global_load_dwordx4 v[4:7], v164, s[38:39]
	global_load_dwordx4 v[20:23], v164, s[38:39] offset:256
	global_load_dwordx4 v[8:11], v165, s[38:39]
	global_load_dwordx4 v[24:27], v165, s[38:39] offset:256
	global_load_dwordx4 v[12:15], v166, s[38:39]
	global_load_dwordx4 v[28:31], v166, s[38:39] offset:256
	global_load_dwordx4 v[16:19], v167, s[38:39]
	global_load_dwordx4 v[32:35], v167, s[38:39] offset:256
	s_add_u32 s38, s38, s46
	s_addc_u32 s39, s39, s55
	s_add_u32 s40, s40, s47
	s_addc_u32 s41, s41, s55
	global_load_dwordx4 v[40:43], v164, s[38:39]
	global_load_dwordx4 v[56:59], v164, s[38:39] offset:256
	global_load_dwordx4 v[44:47], v165, s[38:39]
	global_load_dwordx4 v[60:63], v165, s[38:39] offset:256
	global_load_dwordx4 v[48:51], v166, s[38:39]
	global_load_dwordx4 v[64:67], v166, s[38:39] offset:256
	global_load_dwordx4 v[52:55], v167, s[38:39]
	global_load_dwordx4 v[68:71], v167, s[38:39] offset:256
	s_add_u32 s38, s38, s46
	s_addc_u32 s39, s39, s55
	s_add_u32 s40, s40, s47
	s_addc_u32 s41, s41, s55
.Lm_pro_lj_7:
	s_cmp_eq_u32 s3, 7
	s_cbranch_scc0 .Lm_pro_w7e_5
	s_waitcnt vmcnt(20)
	v_mul_f32_e32 v116, s62, v204
	v_mul_f32_e32 v117, s62, v205
	v_add_f32_e32 v118, v116, v117
	s_nop 1
	v_add_f32_dpp v118, v118, v118 row_shr:1 row_mask:0xf bank_mask:0xf bound_ctrl:0
	s_nop 1
	v_add_f32_dpp v118, v118, v118 row_shr:2 row_mask:0xf bank_mask:0xf bound_ctrl:0
	s_nop 1
	v_add_f32_dpp v118, v118, v118 row_shr:4 row_mask:0xf bank_mask:0xf bound_ctrl:0
	s_nop 1
	v_add_f32_dpp v118, v118, v118 row_shr:8 row_mask:0xf bank_mask:0xf bound_ctrl:0
	s_nop 1
	v_add_f32_dpp v118, v118, v118 row_bcast:15 row_mask:0xa bank_mask:0xf
	s_nop 1
	v_add_f32_dpp v118, v118, v118 row_bcast:31 row_mask:0xc bank_mask:0xf
	s_nop 1
	v_readlane_b32 s97, v118, 63
	v_sub_f32_e32 v122, v118, v117
	v_mov_b32_e32 v123, v118
	s_nop 1
	s_cmp_eq_u32 s51, 0
	s_cbranch_scc1 .Lm_scanf_8
	v_sub_f32_e32 v122, s97, v122
	v_sub_f32_e32 v123, s97, v123
	v_fma_f32 v122, v204, s62, v122
	v_fma_f32 v123, v205, s62, v123

.Lm_pro_w7e_5:
	s_waitcnt lgkmcnt(0)
	s_barrier
	s_cmp_lt_u32 s3, 4
	s_cbranch_scc1 .Lm_pro_wlo_9
	s_waitcnt vmcnt(10)
	ds_read_b32 v116, v172 offset:0
	ds_read_b32 v117, v171 offset:0
	ds_read_b32 v118, v171 offset:512
	ds_read_b32 v152, v171 offset:256
	ds_read_b32 v153, v171 offset:768
	ds_write_b128 v169, v[20:23] offset:0
	ds_write_b128 v169, v[4:7] offset:34816
	ds_write_b128 v169, v[24:27] offset:8704
	ds_write_b128 v169, v[8:11] offset:43520
	ds_write_b128 v169, v[28:31] offset:17408
	ds_write_b128 v169, v[12:15] offset:52224
	ds_write_b128 v169, v[32:35] offset:26112
	ds_write_b128 v169, v[16:19] offset:60928
	v_lshlrev_b32_e32 v120, 16, v36
	v_and_b32_e32 v121, 0xffff0000, v36
	v_lshlrev_b32_e32 v122, 16, v37
	v_and_b32_e32 v123, 0xffff0000, v37
	v_lshlrev_b32_e32 v124, 16, v38
	v_and_b32_e32 v125, 0xffff0000, v38
	v_lshlrev_b32_e32 v126, 16, v39
	v_and_b32_e32 v127, 0xffff0000, v39
	s_waitcnt lgkmcnt(8)
	v_sub_f32_e32 v119, v116, v117
	v_exp_f32_e32 v119, v119
	v_mul_f32_e32 v128, v118, v120
	v_mul_f32_e32 v129, v118, v121
	v_mul_f32_e32 v130, v118, v122
	v_mul_f32_e32 v131, v118, v123
	v_mul_f32_e32 v132, v118, v124
	v_mul_f32_e32 v133, v118, v125
	v_mul_f32_e32 v134, v118, v126
	v_mul_f32_e32 v135, v118, v127
	v_mul_f32_e32 v119, v118, v119
	v_cvt_pk_bf16_f32 v144, v128, v129
	v_cvt_pk_bf16_f32 v145, v130, v131
	v_cvt_pk_bf16_f32 v146, v132, v133
	v_cvt_pk_bf16_f32 v147, v134, v135
	v_mul_f32_e32 v136, v119, v120
	v_mul_f32_e32 v137, v119, v121
	v_mul_f32_e32 v138, v119, v122
	v_mul_f32_e32 v139, v119, v123
	v_mul_f32_e32 v140, v119, v124
	v_mul_f32_e32 v141, v119, v125
	v_mul_f32_e32 v142, v119, v126
	v_mul_f32_e32 v143, v119, v127
	v_cvt_pk_bf16_f32 v148, v136, v137
	v_cvt_pk_bf16_f32 v149, v138, v139
	v_cvt_pk_bf16_f32 v150, v140, v141
	v_cvt_pk_bf16_f32 v151, v142, v143
	ds_write_b128 v170, v[144:147] offset:0
	ds_write_b128 v170, v[148:151] offset:10240
	v_lshlrev_b32_e32 v120, 16, v198
	v_and_b32_e32 v121, 0xffff0000, v198
	v_lshlrev_b32_e32 v122, 16, v199
	v_and_b32_e32 v123, 0xffff0000, v199
	v_lshlrev_b32_e32 v124, 16, v200
	v_and_b32_e32 v125, 0xffff0000, v200
	v_lshlrev_b32_e32 v126, 16, v201
	v_and_b32_e32 v127, 0xffff0000, v201
	v_sub_f32_e32 v119, v116, v152
	v_exp_f32_e32 v119, v119
	v_mul_f32_e32 v128, v153, v120
	v_mul_f32_e32 v129, v153, v121
	v_mul_f32_e32 v130, v153, v122
	v_mul_f32_e32 v131, v153, v123
	v_mul_f32_e32 v132, v153, v124
	v_mul_f32_e32 v133, v153, v125
	v_mul_f32_e32 v134, v153, v126
	v_mul_f32_e32 v135, v153, v127
	v_mul_f32_e32 v119, v153, v119
	v_cvt_pk_bf16_f32 v144, v128, v129
	v_cvt_pk_bf16_f32 v145, v130, v131
	v_cvt_pk_bf16_f32 v146, v132, v133
	v_cvt_pk_bf16_f32 v147, v134, v135
	v_mul_f32_e32 v136, v119, v120
	v_mul_f32_e32 v137, v119, v121
	v_mul_f32_e32 v138, v119, v122
	v_mul_f32_e32 v139, v119, v123
	v_mul_f32_e32 v140, v119, v124
	v_mul_f32_e32 v141, v119, v125
	v_mul_f32_e32 v142, v119, v126
	v_mul_f32_e32 v143, v119, v127
	v_cvt_pk_bf16_f32 v148, v136, v137
	v_cvt_pk_bf16_f32 v149, v138, v139
	v_cvt_pk_bf16_f32 v150, v140, v141
	v_cvt_pk_bf16_f32 v151, v142, v143
	ds_write_b128 v170, v[144:147] offset:4096
	ds_write_b128 v170, v[148:151] offset:14336
	s_branch .Lm_pro_wj_10
.Lm_pro_wlo_9:
	s_waitcnt vmcnt(8)
	ds_write_b128 v169, v[20:23] offset:0
	ds_write_b128 v169, v[4:7] offset:34816
	ds_write_b128 v169, v[24:27] offset:8704
	ds_write_b128 v169, v[8:11] offset:43520
	ds_write_b128 v169, v[28:31] offset:17408
	ds_write_b128 v169, v[12:15] offset:52224
	ds_write_b128 v169, v[32:35] offset:26112
	ds_write_b128 v169, v[16:19] offset:60928
.Lm_pro_wj_10:
	s_waitcnt lgkmcnt(0)
	s_barrier
	s_mov_b32 s50, 0
.Lm_loop:
	s_cmp_lt_u32 s3, 3
	s_cbranch_scc0 .Lm_w3_16
	ds_read_b128 v[176:179], v216 offset:0
	ds_read_b128 v[116:119], v217 offset:34816
	ds_read_b128 v[180:183], v216 offset:32
	ds_read_b128 v[120:123], v217 offset:34848
	ds_read_b128 v[184:187], v216 offset:64
	ds_read_b128 v[124:127], v217 offset:34880
	ds_read_b128 v[188:191], v216 offset:96
	ds_read_b128 v[128:131], v217 offset:34912
	s_waitcnt lgkmcnt(6)
	v_mfma_f32_32x32x16_bf16 v[76:91], v[176:179], v[116:119], 0
	ds_read_b128 v[192:195], v216 offset:128
	ds_read_b128 v[116:119], v217 offset:34944
	global_load_dwordx4 v[4:7], v164, s[38:39]
	s_waitcnt lgkmcnt(6)
	v_mfma_f32_32x32x16_bf16 v[76:91], v[180:183], v[120:123], v[76:91]
	ds_read_b128 v[196:199], v216 offset:160
	ds_read_b128 v[120:123], v217 offset:34976
	global_load_dwordx4 v[20:23], v164, s[38:39] offset:256
	s_waitcnt lgkmcnt(6)
	v_mfma_f32_32x32x16_bf16 v[76:91], v[184:187], v[124:127], v[76:91]
	ds_read_b128 v[200:203], v216 offset:192
	ds_read_b128 v[124:127], v217 offset:35008
	global_load_dwordx4 v[8:11], v165, s[38:39]
	s_waitcnt lgkmcnt(6)
	v_mfma_f32_32x32x16_bf16 v[76:91], v[188:191], v[128:131], v[76:91]
	ds_read_b128 v[204:207], v216 offset:224
	ds_read_b128 v[128:131], v217 offset:35040
	global_load_dwordx4 v[24:27], v165, s[38:39] offset:256
	s_waitcnt lgkmcnt(6)
	v_mfma_f32_32x32x16_bf16 v[76:91], v[192:195], v[116:119], v[76:91]
	ds_read_b128 v[116:119], v217 offset:43520
	global_load_dwordx4 v[12:15], v166, s[38:39]
	ds_read_b128 v[234:237], v222 offset:0
	ds_read_b128 v[238:241], v222 offset:32
	ds_read_b128 v[242:245], v222 offset:64
	ds_read_b128 v[246:249], v222 offset:96
	ds_read_b32 v250, v223 offset:0
	ds_read_b32 v251, v223 offset:128
	s_waitcnt lgkmcnt(11)
	v_mfma_f32_32x32x16_bf16 v[76:91], v[196:199], v[120:123], v[76:91]
	ds_read_b128 v[120:123], v217 offset:43552
	global_load_dwordx4 v[28:31], v166, s[38:39] offset:256
	s_waitcnt lgkmcnt(10)
	v_mfma_f32_32x32x16_bf16 v[76:91], v[200:203], v[124:127], v[76:91]
	ds_read_b128 v[124:127], v217 offset:43584
	global_load_dwordx4 v[16:19], v167, s[38:39]
	s_waitcnt lgkmcnt(9)
	v_mfma_f32_32x32x16_bf16 v[76:91], v[204:207], v[128:131], v[76:91]
	ds_read_b128 v[128:131], v217 offset:43616
	global_load_dwordx4 v[32:35], v167, s[38:39] offset:256
	s_waitcnt lgkmcnt(3)
	s_cmp_eq_u32 s53, 0
	s_cbranch_scc0 .Lm_t0diag_18
	v_mfma_f32_32x32x16_bf16 v[92:107], v[176:179], v[116:119], 0
	ds_read_b128 v[116:119], v217 offset:43648
	v_sub_f32_e32 v132, v234, v250
	v_sub_f32_e32 v133, v235, v250
	v_sub_f32_e32 v134, v236, v250
	v_sub_f32_e32 v135, v237, v250
	v_sub_f32_e32 v136, v238, v250
	v_sub_f32_e32 v137, v239, v250
	v_sub_f32_e32 v138, v240, v250
	s_waitcnt lgkmcnt(3)
	v_mfma_f32_32x32x16_bf16 v[92:107], v[180:183], v[120:123], v[92:107]
	ds_read_b128 v[120:123], v217 offset:43680
	v_sub_f32_e32 v139, v241, v250
	v_sub_f32_e32 v140, v242, v250
	v_sub_f32_e32 v141, v243, v250
	v_sub_f32_e32 v142, v244, v250
	v_sub_f32_e32 v143, v245, v250
	v_sub_f32_e32 v144, v246, v250
	v_sub_f32_e32 v145, v247, v250
	s_waitcnt lgkmcnt(3)
	v_mfma_f32_32x32x16_bf16 v[92:107], v[184:187], v[124:127], v[92:107]
	ds_read_b128 v[124:127], v217 offset:43712
	v_sub_f32_e32 v146, v248, v250
	v_sub_f32_e32 v147, v249, v250
	v_exp_f32_e32 v132, v132
	v_exp_f32_e32 v133, v133
	v_exp_f32_e32 v134, v134
	v_exp_f32_e32 v135, v135
	v_exp_f32_e32 v136, v136
	s_waitcnt lgkmcnt(3)
	v_mfma_f32_32x32x16_bf16 v[92:107], v[188:191], v[128:131], v[92:107]
	ds_read_b128 v[128:131], v217 offset:43744
	v_exp_f32_e32 v137, v137
	v_exp_f32_e32 v138, v138
	v_exp_f32_e32 v139, v139
	v_exp_f32_e32 v140, v140
	v_exp_f32_e32 v141, v141
	v_exp_f32_e32 v142, v142
	v_exp_f32_e32 v143, v143
	s_waitcnt lgkmcnt(3)
	v_mfma_f32_32x32x16_bf16 v[92:107], v[192:195], v[116:119], v[92:107]
	v_exp_f32_e32 v144, v144
	v_exp_f32_e32 v145, v145
	v_exp_f32_e32 v146, v146
	v_exp_f32_e32 v147, v147
	v_mul_f32_e32 v76, v76, v132
	v_mul_f32_e32 v77, v77, v133
	v_mul_f32_e32 v78, v78, v134
	s_waitcnt lgkmcnt(2)
	v_mfma_f32_32x32x16_bf16 v[92:107], v[196:199], v[120:123], v[92:107]
	v_mul_f32_e32 v79, v79, v135
	v_mul_f32_e32 v80, v80, v136
	v_mul_f32_e32 v81, v81, v137
	v_mul_f32_e32 v82, v82, v138
	v_mul_f32_e32 v83, v83, v139
	v_mul_f32_e32 v84, v84, v140
	v_mul_f32_e32 v85, v85, v141
	s_waitcnt lgkmcnt(1)
	v_mfma_f32_32x32x16_bf16 v[92:107], v[200:203], v[124:127], v[92:107]
	v_mul_f32_e32 v86, v86, v142
	v_mul_f32_e32 v87, v87, v143
	v_mul_f32_e32 v88, v88, v144
	v_mul_f32_e32 v89, v89, v145
	v_mul_f32_e32 v90, v90, v146
	v_mul_f32_e32 v91, v91, v147
	v_cvt_pk_bf16_f32 v148, v76, v77
	s_waitcnt lgkmcnt(0)
	v_mfma_f32_32x32x16_bf16 v[92:107], v[204:207], v[128:131], v[92:107]
	v_cvt_pk_bf16_f32 v149, v78, v79
	v_cvt_pk_bf16_f32 v150, v80, v81
	v_cvt_pk_bf16_f32 v151, v82, v83
	v_cvt_pk_bf16_f32 v152, v84, v85
	v_cvt_pk_bf16_f32 v153, v86, v87
	v_cvt_pk_bf16_f32 v154, v88, v89
	v_cvt_pk_bf16_f32 v155, v90, v91
	s_branch .Lm_t0join_19
.Lm_t0diag_18:
	v_mfma_f32_32x32x16_bf16 v[92:107], v[176:179], v[116:119], 0
	ds_read_b128 v[116:119], v217 offset:43648
	v_sub_f32_e32 v132, v234, v250
	v_sub_f32_e32 v133, v235, v250
	v_sub_f32_e32 v134, v236, v250
	v_sub_f32_e32 v135, v237, v250
	v_sub_f32_e32 v136, v238, v250
	v_sub_f32_e32 v137, v239, v250
	v_sub_f32_e32 v138, v240, v250
	v_sub_f32_e32 v139, v241, v250
	v_sub_f32_e32 v140, v242, v250
	s_waitcnt lgkmcnt(3)
	v_mfma_f32_32x32x16_bf16 v[92:107], v[180:183], v[120:123], v[92:107]
	ds_read_b128 v[120:123], v217 offset:43680
	v_sub_f32_e32 v141, v243, v250
	v_sub_f32_e32 v142, v244, v250
	v_sub_f32_e32 v143, v245, v250
	v_sub_f32_e32 v144, v246, v250
	v_sub_f32_e32 v145, v247, v250
	v_sub_f32_e32 v146, v248, v250
	v_sub_f32_e32 v147, v249, v250
	v_exp_f32_e32 v132, v132
	v_exp_f32_e32 v133, v133
	s_waitcnt lgkmcnt(3)
	v_mfma_f32_32x32x16_bf16 v[92:107], v[184:187], v[124:127], v[92:107]
	ds_read_b128 v[124:127], v217 offset:43712
	v_exp_f32_e32 v134, v134
	v_exp_f32_e32 v135, v135
	v_exp_f32_e32 v136, v136
	v_exp_f32_e32 v137, v137
	v_exp_f32_e32 v138, v138
	v_exp_f32_e32 v139, v139
	v_exp_f32_e32 v140, v140
	v_exp_f32_e32 v141, v141
	v_exp_f32_e32 v142, v142
	s_waitcnt lgkmcnt(3)
	v_mfma_f32_32x32x16_bf16 v[92:107], v[188:191], v[128:131], v[92:107]
	ds_read_b128 v[128:131], v217 offset:43744
	v_exp_f32_e32 v143, v143
	v_exp_f32_e32 v144, v144
	v_exp_f32_e32 v145, v145
	v_exp_f32_e32 v146, v146
	v_exp_f32_e32 v147, v147
	v_mul_f32_e32 v76, v76, v132
	v_mul_f32_e32 v77, v77, v133
	v_mul_f32_e32 v78, v78, v134
	v_mul_f32_e32 v79, v79, v135
	s_waitcnt lgkmcnt(3)
	v_mfma_f32_32x32x16_bf16 v[92:107], v[192:195], v[116:119], v[92:107]
	v_mul_f32_e32 v80, v80, v136
	v_mul_f32_e32 v81, v81, v137
	v_mul_f32_e32 v82, v82, v138
	v_mul_f32_e32 v83, v83, v139
	v_mul_f32_e32 v84, v84, v140
	v_mul_f32_e32 v85, v85, v141
	v_mul_f32_e32 v86, v86, v142
	v_mul_f32_e32 v87, v87, v143
	v_mul_f32_e32 v88, v88, v144
	s_waitcnt lgkmcnt(2)
	v_mfma_f32_32x32x16_bf16 v[92:107], v[196:199], v[120:123], v[92:107]
	v_mul_f32_e32 v89, v89, v145
	v_mul_f32_e32 v90, v90, v146
	v_mul_f32_e32 v91, v91, v147
	v_cndmask_b32_e64 v76, 0, v76, s[64:65]
	v_cndmask_b32_e64 v77, 0, v77, s[66:67]
	v_cndmask_b32_e64 v78, 0, v78, s[68:69]
	v_cndmask_b32_e64 v79, 0, v79, s[70:71]
	v_cndmask_b32_e64 v80, 0, v80, s[72:73]
	v_cndmask_b32_e64 v81, 0, v81, s[74:75]
	s_waitcnt lgkmcnt(1)
	v_mfma_f32_32x32x16_bf16 v[92:107], v[200:203], v[124:127], v[92:107]
	v_cndmask_b32_e64 v82, 0, v82, s[76:77]
	v_cndmask_b32_e64 v83, 0, v83, s[78:79]
	v_cndmask_b32_e64 v84, 0, v84, s[80:81]
	v_cndmask_b32_e64 v85, 0, v85, s[82:83]
	v_cndmask_b32_e64 v86, 0, v86, s[84:85]
	v_cndmask_b32_e64 v87, 0, v87, s[86:87]
	v_cndmask_b32_e64 v88, 0, v88, s[88:89]
	v_cndmask_b32_e64 v89, 0, v89, s[90:91]
	v_cndmask_b32_e64 v90, 0, v90, s[92:93]
	s_waitcnt lgkmcnt(0)
	v_mfma_f32_32x32x16_bf16 v[92:107], v[204:207], v[128:131], v[92:107]
	v_cndmask_b32_e64 v91, 0, v91, s[94:95]
	v_cvt_pk_bf16_f32 v148, v76, v77
	v_cvt_pk_bf16_f32 v149, v78, v79
	v_cvt_pk_bf16_f32 v150, v80, v81
	v_cvt_pk_bf16_f32 v151, v82, v83
	v_cvt_pk_bf16_f32 v152, v84, v85
	v_cvt_pk_bf16_f32 v153, v86, v87
	v_cvt_pk_bf16_f32 v154, v88, v89
	v_cvt_pk_bf16_f32 v155, v90, v91

.Lm_w3_16:
	s_cmp_eq_u32 s3, 3
	s_cbranch_scc0 .Lm_w456_17
	ds_read_b128 v[116:119], v216 offset:0
	ds_read_b128 v[120:123], v217 offset:34816
	ds_read_b128 v[128:131], v216 offset:32
	ds_read_b128 v[132:135], v217 offset:34848
	ds_read_b128 v[140:143], v216 offset:64
	ds_read_b128 v[144:147], v217 offset:34880
	ds_read_b128 v[152:155], v216 offset:96
	ds_read_b128 v[156:159], v217 offset:34912
	s_waitcnt lgkmcnt(6)
	v_mfma_f32_32x32x16_bf16 v[76:91], v[116:119], v[120:123], 0
	ds_read_b128 v[116:119], v216 offset:128
	ds_read_b128 v[120:123], v217 offset:34944
	global_load_dwordx4 v[4:7], v164, s[38:39]
	s_waitcnt lgkmcnt(6)
	v_mfma_f32_32x32x16_bf16 v[76:91], v[128:131], v[132:135], v[76:91]
	ds_read_b128 v[128:131], v216 offset:160
	ds_read_b128 v[132:135], v217 offset:34976
	global_load_dwordx4 v[20:23], v164, s[38:39] offset:256
	s_waitcnt lgkmcnt(6)
	v_mfma_f32_32x32x16_bf16 v[76:91], v[140:143], v[144:147], v[76:91]
	ds_read_b128 v[140:143], v216 offset:192
	ds_read_b128 v[144:147], v217 offset:35008
	global_load_dwordx4 v[8:11], v165, s[38:39]
	s_waitcnt lgkmcnt(6)
	v_mfma_f32_32x32x16_bf16 v[76:91], v[152:155], v[156:159], v[76:91]
	ds_read_b128 v[152:155], v216 offset:224
	ds_read_b128 v[156:159], v217 offset:35040
	global_load_dwordx4 v[24:27], v165, s[38:39] offset:256
	s_waitcnt lgkmcnt(6)
	v_mfma_f32_32x32x16_bf16 v[76:91], v[116:119], v[120:123], v[76:91]
	global_load_dwordx4 v[12:15], v166, s[38:39]
	ds_read_b128 v[234:237], v222 offset:0
	ds_read_b128 v[238:241], v222 offset:32
	ds_read_b128 v[242:245], v222 offset:64
	ds_read_b128 v[246:249], v222 offset:96
	ds_read_b32 v250, v223 offset:0
	s_waitcnt lgkmcnt(9)
	v_mfma_f32_32x32x16_bf16 v[76:91], v[128:131], v[132:135], v[76:91]
	global_load_dwordx4 v[28:31], v166, s[38:39] offset:256
	s_waitcnt lgkmcnt(7)
	v_mfma_f32_32x32x16_bf16 v[76:91], v[140:143], v[144:147], v[76:91]
	global_load_dwordx4 v[16:19], v167, s[38:39]
	s_waitcnt lgkmcnt(5)
	v_mfma_f32_32x32x16_bf16 v[76:91], v[152:155], v[156:159], v[76:91]
	global_load_dwordx4 v[32:35], v167, s[38:39] offset:256
	s_add_u32 s38, s38, s46
	s_addc_u32 s39, s39, s55
	s_add_u32 s40, s40, s47
	s_addc_u32 s41, s41, s55
	ds_read_b128 v[176:179], v173 offset:0
	ds_read_b128 v[180:183], v173 offset:32
	ds_read_b128 v[184:187], v173 offset:64
	ds_read_b128 v[188:191], v173 offset:96
	ds_read_b128 v[192:195], v173 offset:128
	ds_read_b128 v[196:199], v173 offset:160
	ds_read_b128 v[200:203], v173 offset:192
	ds_read_b128 v[204:207], v173 offset:224
	ds_read_b32 v2, v211 offset:0
	s_waitcnt lgkmcnt(9)
	v_sub_f32_e32 v116, v234, v250
	v_sub_f32_e32 v117, v235, v250
	v_sub_f32_e32 v118, v236, v250
	v_sub_f32_e32 v119, v237, v250
	v_sub_f32_e32 v120, v238, v250
	v_sub_f32_e32 v121, v239, v250
	v_sub_f32_e32 v122, v240, v250
	v_sub_f32_e32 v123, v241, v250
	v_sub_f32_e32 v124, v242, v250
	v_sub_f32_e32 v125, v243, v250
	v_sub_f32_e32 v126, v244, v250
	v_sub_f32_e32 v127, v245, v250
	v_sub_f32_e32 v128, v246, v250
	v_sub_f32_e32 v129, v247, v250
	v_sub_f32_e32 v130, v248, v250
	v_sub_f32_e32 v131, v249, v250
	v_exp_f32_e32 v116, v116
	v_exp_f32_e32 v117, v117
	v_exp_f32_e32 v118, v118
	v_exp_f32_e32 v119, v119
	v_exp_f32_e32 v120, v120
	v_exp_f32_e32 v121, v121
	v_exp_f32_e32 v122, v122
	v_exp_f32_e32 v123, v123
	v_exp_f32_e32 v124, v124
	v_exp_f32_e32 v125, v125
	v_exp_f32_e32 v126, v126
	v_exp_f32_e32 v127, v127
	v_exp_f32_e32 v128, v128
	v_exp_f32_e32 v129, v129
	v_exp_f32_e32 v130, v130
	v_exp_f32_e32 v131, v131
	v_mul_f32_e32 v76, v76, v116
	v_mul_f32_e32 v77, v77, v117
	v_mul_f32_e32 v78, v78, v118
	v_mul_f32_e32 v79, v79, v119
	v_mul_f32_e32 v80, v80, v120
	v_mul_f32_e32 v81, v81, v121
	v_mul_f32_e32 v82, v82, v122
	v_mul_f32_e32 v83, v83, v123
	v_mul_f32_e32 v84, v84, v124
	v_mul_f32_e32 v85, v85, v125
	v_mul_f32_e32 v86, v86, v126
	v_mul_f32_e32 v87, v87, v127
	v_mul_f32_e32 v88, v88, v128
	v_mul_f32_e32 v89, v89, v129
	v_mul_f32_e32 v90, v90, v130
	v_mul_f32_e32 v91, v91, v131
	s_cmp_eq_u32 s53, 0
	s_cbranch_scc1 .Lm_nodiag_22
	v_cndmask_b32_e64 v76, 0, v76, s[64:65]
	v_cndmask_b32_e64 v77, 0, v77, s[66:67]
	v_cndmask_b32_e64 v78, 0, v78, s[68:69]
	v_cndmask_b32_e64 v79, 0, v79, s[70:71]
	v_cndmask_b32_e64 v80, 0, v80, s[72:73]
	v_cndmask_b32_e64 v81, 0, v81, s[74:75]
	v_cndmask_b32_e64 v82, 0, v82, s[76:77]
	v_cndmask_b32_e64 v83, 0, v83, s[78:79]
	v_cndmask_b32_e64 v84, 0, v84, s[80:81]
	v_cndmask_b32_e64 v85, 0, v85, s[82:83]
	v_cndmask_b32_e64 v86, 0, v86, s[84:85]
	v_cndmask_b32_e64 v87, 0, v87, s[86:87]
	v_cndmask_b32_e64 v88, 0, v88, s[88:89]
	v_cndmask_b32_e64 v89, 0, v89, s[90:91]
	v_cndmask_b32_e64 v90, 0, v90, s[92:93]
	v_cndmask_b32_e64 v91, 0, v91, s[94:95]

.Lm_w456_17:
	s_cmp_lt_u32 s3, 7
	s_cbranch_scc0 .Lm_g0_12
	ds_read_b128 v[116:119], v216 offset:0
	ds_read_b128 v[120:123], v217 offset:34816
	ds_read_b128 v[128:131], v216 offset:32
	ds_read_b128 v[132:135], v217 offset:34848
	ds_read_b128 v[140:143], v216 offset:64
	ds_read_b128 v[144:147], v217 offset:34880
	ds_read_b128 v[152:155], v216 offset:96
	ds_read_b128 v[156:159], v217 offset:34912
	s_waitcnt lgkmcnt(6)
	v_mfma_f32_32x32x16_bf16 v[76:91], v[116:119], v[120:123], 0
	ds_read_b128 v[116:119], v216 offset:128
	ds_read_b128 v[120:123], v217 offset:34944
	global_load_dwordx4 v[4:7], v164, s[38:39]
	s_waitcnt lgkmcnt(6)
	v_mfma_f32_32x32x16_bf16 v[76:91], v[128:131], v[132:135], v[76:91]
	ds_read_b128 v[128:131], v216 offset:160
	ds_read_b128 v[132:135], v217 offset:34976
	global_load_dwordx4 v[20:23], v164, s[38:39] offset:256
	s_waitcnt lgkmcnt(6)
	v_mfma_f32_32x32x16_bf16 v[76:91], v[140:143], v[144:147], v[76:91]
	ds_read_b128 v[140:143], v216 offset:192
	ds_read_b128 v[144:147], v217 offset:35008
	global_load_dwordx4 v[8:11], v165, s[38:39]
	s_waitcnt lgkmcnt(6)
	v_mfma_f32_32x32x16_bf16 v[76:91], v[152:155], v[156:159], v[76:91]
	ds_read_b128 v[152:155], v216 offset:224
	ds_read_b128 v[156:159], v217 offset:35040
	global_load_dwordx4 v[24:27], v165, s[38:39] offset:256
	s_waitcnt lgkmcnt(6)
	v_mfma_f32_32x32x16_bf16 v[76:91], v[116:119], v[120:123], v[76:91]
	global_load_dwordx4 v[12:15], v166, s[38:39]
	ds_read_b128 v[234:237], v222 offset:0
	ds_read_b128 v[238:241], v222 offset:32
	ds_read_b128 v[242:245], v222 offset:64
	ds_read_b128 v[246:249], v222 offset:96
	ds_read_b32 v250, v223 offset:0
	s_waitcnt lgkmcnt(9)
	v_mfma_f32_32x32x16_bf16 v[76:91], v[128:131], v[132:135], v[76:91]
	global_load_dwordx4 v[28:31], v166, s[38:39] offset:256
	s_waitcnt lgkmcnt(7)
	v_mfma_f32_32x32x16_bf16 v[76:91], v[140:143], v[144:147], v[76:91]
	global_load_dwordx4 v[16:19], v167, s[38:39]
	s_waitcnt lgkmcnt(5)
	v_mfma_f32_32x32x16_bf16 v[76:91], v[152:155], v[156:159], v[76:91]
	global_load_dwordx4 v[32:35], v167, s[38:39] offset:256
	global_load_dwordx4 v[36:39], v168, s[40:41]
	global_load_dwordx4 v[198:201], v202, s[40:41]
	s_add_u32 s38, s38, s46
	s_addc_u32 s39, s39, s55
	s_add_u32 s40, s40, s47
	s_addc_u32 s41, s41, s55
	s_waitcnt lgkmcnt(0)
	ds_read_b32 v1, v172 offset:0
	ds_read_b64_tr_b16 v[116:117], v193 offset:0
	ds_read_b64_tr_b16 v[118:119], v193 offset:1088
	ds_read_b64_tr_b16 v[120:121], v192 offset:0
	ds_read_b64_tr_b16 v[122:123], v192 offset:256
	ds_read_b64_tr_b16 v[124:125], v193 offset:4352
	ds_read_b64_tr_b16 v[126:127], v193 offset:5440
	ds_read_b64_tr_b16 v[128:129], v192 offset:1024
	ds_read_b64_tr_b16 v[130:131], v192 offset:1280
	ds_read_b64_tr_b16 v[132:133], v193 offset:8704
	ds_read_b64_tr_b16 v[134:135], v193 offset:9792
	ds_read_b64_tr_b16 v[136:137], v192 offset:2048
	ds_read_b64_tr_b16 v[138:139], v192 offset:2304
	s_waitcnt lgkmcnt(12)
	v_exp_f32_e32 v1, v1
	s_nop 0
	v_mul_f32_e32 v176, v176, v1
	v_mul_f32_e32 v177, v177, v1
	v_mul_f32_e32 v178, v178, v1
	v_mul_f32_e32 v179, v179, v1
	v_mul_f32_e32 v180, v180, v1
	v_mul_f32_e32 v181, v181, v1
	v_mul_f32_e32 v182, v182, v1
	v_mul_f32_e32 v183, v183, v1
	v_mul_f32_e32 v184, v184, v1
	v_mul_f32_e32 v185, v185, v1
	v_mul_f32_e32 v186, v186, v1
	v_mul_f32_e32 v187, v187, v1
	v_mul_f32_e32 v188, v188, v1
	v_mul_f32_e32 v189, v189, v1
	v_mul_f32_e32 v190, v190, v1
	v_mul_f32_e32 v191, v191, v1
	s_nop 1
	s_cmp_eq_u32 s53, 0
	s_cbranch_scc0 .Lm_sdiag_23
	s_waitcnt lgkmcnt(8)
	v_mfma_f32_32x32x16_bf16 v[176:191], v[116:119], v[120:123], v[176:191]
	ds_read_b64_tr_b16 v[116:117], v193 offset:13056
	ds_read_b64_tr_b16 v[118:119], v193 offset:14144
	ds_read_b64_tr_b16 v[120:121], v192 offset:3072
	ds_read_b64_tr_b16 v[122:123], v192 offset:3328
	v_sub_f32_e32 v140, v234, v250
	v_sub_f32_e32 v141, v235, v250
	v_sub_f32_e32 v142, v236, v250
	v_sub_f32_e32 v143, v237, v250
	v_sub_f32_e32 v144, v238, v250
	v_sub_f32_e32 v145, v239, v250
	v_sub_f32_e32 v146, v240, v250
	s_waitcnt lgkmcnt(8)
	v_mfma_f32_32x32x16_bf16 v[176:191], v[124:127], v[128:131], v[176:191]
	ds_read_b64_tr_b16 v[124:125], v193 offset:17408
	ds_read_b64_tr_b16 v[126:127], v193 offset:18496
	ds_read_b64_tr_b16 v[128:129], v192 offset:4096
	ds_read_b64_tr_b16 v[130:131], v192 offset:4352
	v_sub_f32_e32 v147, v241, v250
	v_sub_f32_e32 v148, v242, v250
	v_sub_f32_e32 v149, v243, v250
	v_sub_f32_e32 v150, v244, v250
	v_sub_f32_e32 v151, v245, v250
	v_sub_f32_e32 v152, v246, v250
	v_sub_f32_e32 v153, v247, v250
	s_waitcnt lgkmcnt(8)
	v_mfma_f32_32x32x16_bf16 v[176:191], v[132:135], v[136:139], v[176:191]
	ds_read_b64_tr_b16 v[132:133], v193 offset:21760
	ds_read_b64_tr_b16 v[134:135], v193 offset:22848
	ds_read_b64_tr_b16 v[136:137], v192 offset:5120
	ds_read_b64_tr_b16 v[138:139], v192 offset:5376
	v_sub_f32_e32 v154, v248, v250
	v_sub_f32_e32 v155, v249, v250
	v_exp_f32_e32 v140, v140
	v_exp_f32_e32 v141, v141
	v_exp_f32_e32 v142, v142
	v_exp_f32_e32 v143, v143
	v_exp_f32_e32 v144, v144
	s_waitcnt lgkmcnt(8)
	v_mfma_f32_32x32x16_bf16 v[176:191], v[116:119], v[120:123], v[176:191]
	ds_read_b64_tr_b16 v[116:117], v193 offset:26112
	ds_read_b64_tr_b16 v[118:119], v193 offset:27200
	ds_read_b64_tr_b16 v[120:121], v192 offset:6144
	ds_read_b64_tr_b16 v[122:123], v192 offset:6400
	v_exp_f32_e32 v145, v145
	v_exp_f32_e32 v146, v146
	v_exp_f32_e32 v147, v147
	v_exp_f32_e32 v148, v148
	v_exp_f32_e32 v149, v149
	v_exp_f32_e32 v150, v150
	v_exp_f32_e32 v151, v151
	s_waitcnt lgkmcnt(8)
	v_mfma_f32_32x32x16_bf16 v[176:191], v[124:127], v[128:131], v[176:191]
	ds_read_b64_tr_b16 v[124:125], v193 offset:30464
	ds_read_b64_tr_b16 v[126:127], v193 offset:31552
	ds_read_b64_tr_b16 v[128:129], v192 offset:7168
	ds_read_b64_tr_b16 v[130:131], v192 offset:7424
	v_exp_f32_e32 v152, v152
	v_exp_f32_e32 v153, v153
	v_exp_f32_e32 v154, v154
	v_exp_f32_e32 v155, v155
	v_mul_f32_e32 v76, v76, v140
	v_mul_f32_e32 v77, v77, v141
	v_mul_f32_e32 v78, v78, v142
	s_waitcnt lgkmcnt(8)
	v_mfma_f32_32x32x16_bf16 v[176:191], v[132:135], v[136:139], v[176:191]
	v_mul_f32_e32 v79, v79, v143
	v_mul_f32_e32 v80, v80, v144
	v_mul_f32_e32 v81, v81, v145
	v_mul_f32_e32 v82, v82, v146
	v_mul_f32_e32 v83, v83, v147
	v_mul_f32_e32 v84, v84, v148
	v_mul_f32_e32 v85, v85, v149
	s_waitcnt lgkmcnt(4)
	v_mfma_f32_32x32x16_bf16 v[176:191], v[116:119], v[120:123], v[176:191]
	v_mul_f32_e32 v86, v86, v150
	v_mul_f32_e32 v87, v87, v151
	v_mul_f32_e32 v88, v88, v152
	v_mul_f32_e32 v89, v89, v153
	v_mul_f32_e32 v90, v90, v154
	v_mul_f32_e32 v91, v91, v155
	v_cvt_pk_bf16_f32 v156, v76, v77
	s_waitcnt lgkmcnt(0)
	v_mfma_f32_32x32x16_bf16 v[176:191], v[124:127], v[128:131], v[176:191]
	v_cvt_pk_bf16_f32 v157, v78, v79
	v_cvt_pk_bf16_f32 v158, v80, v81
	v_cvt_pk_bf16_f32 v159, v82, v83
	v_cvt_pk_bf16_f32 v160, v84, v85
	v_cvt_pk_bf16_f32 v161, v86, v87
	v_cvt_pk_bf16_f32 v162, v88, v89
	v_cvt_pk_bf16_f32 v163, v90, v91
	s_branch .Lm_sjoin_24

.Lm_g0_12:
	ds_read_b32 v1, v172 offset:0
	ds_read_b64_tr_b16 v[116:117], v193 offset:0
	ds_read_b64_tr_b16 v[118:119], v193 offset:1088
	ds_read_b64_tr_b16 v[120:121], v192 offset:0
	ds_read_b64_tr_b16 v[122:123], v192 offset:256
	ds_read_b64_tr_b16 v[124:125], v193 offset:4352
	ds_read_b64_tr_b16 v[126:127], v193 offset:5440
	ds_read_b64_tr_b16 v[128:129], v192 offset:1024
	ds_read_b64_tr_b16 v[130:131], v192 offset:1280
	ds_read_b64_tr_b16 v[132:133], v193 offset:8704
	ds_read_b64_tr_b16 v[134:135], v193 offset:9792
	ds_read_b64_tr_b16 v[136:137], v192 offset:2048
	ds_read_b64_tr_b16 v[138:139], v192 offset:2304
	s_waitcnt lgkmcnt(12)
	v_exp_f32_e32 v1, v1
	s_nop 0
	v_mul_f32_e32 v176, v176, v1
	v_mul_f32_e32 v177, v177, v1
	v_mul_f32_e32 v178, v178, v1
	v_mul_f32_e32 v179, v179, v1
	v_mul_f32_e32 v180, v180, v1
	v_mul_f32_e32 v181, v181, v1
	v_mul_f32_e32 v182, v182, v1
	v_mul_f32_e32 v183, v183, v1
	v_mul_f32_e32 v184, v184, v1
	v_mul_f32_e32 v185, v185, v1
	v_mul_f32_e32 v186, v186, v1
	v_mul_f32_e32 v187, v187, v1
	v_mul_f32_e32 v188, v188, v1
	v_mul_f32_e32 v189, v189, v1
	v_mul_f32_e32 v190, v190, v1
	v_mul_f32_e32 v191, v191, v1
	s_nop 1
	s_waitcnt lgkmcnt(8)
	v_mfma_f32_32x32x16_bf16 v[176:191], v[116:119], v[120:123], v[176:191]
	ds_read_b64_tr_b16 v[116:117], v193 offset:13056
	ds_read_b64_tr_b16 v[118:119], v193 offset:14144
	ds_read_b64_tr_b16 v[120:121], v192 offset:3072
	ds_read_b64_tr_b16 v[122:123], v192 offset:3328
	global_load_dwordx4 v[4:7], v164, s[38:39]
	s_waitcnt lgkmcnt(8)
	v_mfma_f32_32x32x16_bf16 v[176:191], v[124:127], v[128:131], v[176:191]
	ds_read_b64_tr_b16 v[124:125], v193 offset:17408
	ds_read_b64_tr_b16 v[126:127], v193 offset:18496
	ds_read_b64_tr_b16 v[128:129], v192 offset:4096
	ds_read_b64_tr_b16 v[130:131], v192 offset:4352
	global_load_dwordx4 v[20:23], v164, s[38:39] offset:256
	s_waitcnt lgkmcnt(8)
	v_mfma_f32_32x32x16_bf16 v[176:191], v[132:135], v[136:139], v[176:191]
	ds_read_b64_tr_b16 v[132:133], v193 offset:21760
	ds_read_b64_tr_b16 v[134:135], v193 offset:22848
	ds_read_b64_tr_b16 v[136:137], v192 offset:5120
	ds_read_b64_tr_b16 v[138:139], v192 offset:5376
	global_load_dwordx4 v[8:11], v165, s[38:39]
	s_waitcnt lgkmcnt(8)
	v_mfma_f32_32x32x16_bf16 v[176:191], v[116:119], v[120:123], v[176:191]
	ds_read_b64_tr_b16 v[116:117], v193 offset:26112
	ds_read_b64_tr_b16 v[118:119], v193 offset:27200
	ds_read_b64_tr_b16 v[120:121], v192 offset:6144
	ds_read_b64_tr_b16 v[122:123], v192 offset:6400
	global_load_dwordx4 v[24:27], v165, s[38:39] offset:256
	s_waitcnt lgkmcnt(8)
	v_mfma_f32_32x32x16_bf16 v[176:191], v[124:127], v[128:131], v[176:191]
	ds_read_b64_tr_b16 v[124:125], v193 offset:30464
	ds_read_b64_tr_b16 v[126:127], v193 offset:31552
	ds_read_b64_tr_b16 v[128:129], v192 offset:7168
	ds_read_b64_tr_b16 v[130:131], v192 offset:7424
	global_load_dwordx4 v[12:15], v166, s[38:39]
	s_waitcnt lgkmcnt(8)
	v_mfma_f32_32x32x16_bf16 v[176:191], v[132:135], v[136:139], v[176:191]
	global_load_dwordx4 v[28:31], v166, s[38:39] offset:256
	s_waitcnt lgkmcnt(4)
	v_mfma_f32_32x32x16_bf16 v[176:191], v[116:119], v[120:123], v[176:191]
	global_load_dwordx4 v[16:19], v167, s[38:39]
	s_waitcnt lgkmcnt(0)
	v_mfma_f32_32x32x16_bf16 v[176:191], v[124:127], v[128:131], v[176:191]
	global_load_dwordx4 v[32:35], v167, s[38:39] offset:256
	global_load_dwordx4 v[36:39], v168, s[40:41]
	global_load_dwordx4 v[198:201], v202, s[40:41]
	s_add_u32 s38, s38, s46
	s_addc_u32 s39, s39, s55
	s_add_u32 s40, s40, s47
	s_addc_u32 s41, s41, s55
	s_nop 7
	s_nop 3
	v_cvt_pk_bf16_f32 v140, v176, v177
	v_cvt_pk_bf16_f32 v141, v178, v179
	v_cvt_pk_bf16_f32 v142, v180, v181
	v_cvt_pk_bf16_f32 v143, v182, v183
	v_cvt_pk_bf16_f32 v144, v184, v185
	v_cvt_pk_bf16_f32 v145, v186, v187
	v_cvt_pk_bf16_f32 v146, v188, v189
	v_cvt_pk_bf16_f32 v147, v190, v191
	ds_write_b64 v194, v[140:141] offset:8704
	ds_write_b64 v194, v[142:143] offset:8720
	ds_write_b64 v194, v[144:145] offset:8736
	ds_write_b64 v194, v[146:147] offset:8752
	s_cmp_lt_u32 s50, 63
	s_cbranch_scc0 .Lm_noscan_25
	s_waitcnt vmcnt(10)
	v_mul_f32_e32 v116, s62, v204
	v_mul_f32_e32 v117, s62, v205
	v_add_f32_e32 v118, v116, v117
	s_nop 1
	v_add_f32_dpp v118, v118, v118 row_shr:1 row_mask:0xf bank_mask:0xf bound_ctrl:0
	s_nop 1
	v_add_f32_dpp v118, v118, v118 row_shr:2 row_mask:0xf bank_mask:0xf bound_ctrl:0
	s_nop 1
	v_add_f32_dpp v118, v118, v118 row_shr:4 row_mask:0xf bank_mask:0xf bound_ctrl:0
	s_nop 1
	v_add_f32_dpp v118, v118, v118 row_shr:8 row_mask:0xf bank_mask:0xf bound_ctrl:0
	s_nop 1
	v_add_f32_dpp v118, v118, v118 row_bcast:15 row_mask:0xa bank_mask:0xf
	s_nop 1
	v_add_f32_dpp v118, v118, v118 row_bcast:31 row_mask:0xc bank_mask:0xf
	s_nop 1
	v_readlane_b32 s97, v118, 63
	v_sub_f32_e32 v122, v118, v117
	v_mov_b32_e32 v123, v118
	s_nop 1
	s_cmp_eq_u32 s51, 0
	s_cbranch_scc1 .Lm_scanf_26
	v_sub_f32_e32 v122, s97, v122
	v_sub_f32_e32 v123, s97, v123
	v_fma_f32 v122, v204, s62, v122
	v_fma_f32 v123, v205, s62, v123

.Lm_noscan_25:
.Lm_adone_15:
	s_waitcnt lgkmcnt(0)
	s_barrier
	s_cmp_lt_u32 s3, 4
	s_cbranch_scc0 .Lm_noy_27
	ds_read_b128 v[116:119], v210 offset:0
	ds_read_b128 v[120:123], v210 offset:32
	ds_read_b128 v[124:127], v210 offset:64
	ds_read_b128 v[128:131], v210 offset:96
	ds_read_b128 v[132:135], v210 offset:128
	ds_read_b128 v[136:139], v210 offset:160
	ds_read_b128 v[140:143], v210 offset:192
	ds_read_b128 v[144:147], v210 offset:224
	ds_read_b64_tr_b16 v[148:149], v208 offset:0
	ds_read_b64_tr_b16 v[150:151], v208 offset:256
	ds_read_b64_tr_b16 v[152:153], v209 offset:0
	ds_read_b64_tr_b16 v[154:155], v110 offset:0
	s_waitcnt lgkmcnt(11)
	v_mfma_f32_32x32x16_bf16 v[92:107], v[116:119], v[176:179], 0
	s_waitcnt lgkmcnt(10)
	v_mfma_f32_32x32x16_bf16 v[92:107], v[120:123], v[180:183], v[92:107]
	ds_read_b64_tr_b16 v[156:157], v208 offset:1024
	ds_read_b64_tr_b16 v[158:159], v208 offset:1280
	ds_read_b64_tr_b16 v[160:161], v209 offset:4096
	ds_read_b64_tr_b16 v[162:163], v110 offset:4096
	s_waitcnt lgkmcnt(13)
	v_mfma_f32_32x32x16_bf16 v[92:107], v[124:127], v[184:187], v[92:107]
	s_waitcnt lgkmcnt(12)
	v_mfma_f32_32x32x16_bf16 v[92:107], v[128:131], v[188:191], v[92:107]
	s_waitcnt lgkmcnt(11)
	v_mfma_f32_32x32x16_bf16 v[92:107], v[132:135], v[192:195], v[92:107]
	ds_read_b64_tr_b16 v[116:117], v208 offset:2048
	ds_read_b64_tr_b16 v[118:119], v208 offset:2304
	ds_read_b64_tr_b16 v[120:121], v209 offset:8192
	ds_read_b64_tr_b16 v[122:123], v110 offset:8192
	s_waitcnt lgkmcnt(14)
	v_mfma_f32_32x32x16_bf16 v[92:107], v[136:139], v[196:199], v[92:107]
	s_waitcnt lgkmcnt(13)
	v_mfma_f32_32x32x16_bf16 v[92:107], v[140:143], v[200:203], v[92:107]
	s_waitcnt lgkmcnt(12)
	v_mfma_f32_32x32x16_bf16 v[92:107], v[144:147], v[204:207], v[92:107]
	s_waitcnt lgkmcnt(8)
	v_mfma_f32_32x32x16_bf16 v[76:91], v[148:151], v[152:155], 0
	ds_read_b64_tr_b16 v[124:125], v208 offset:3072
	ds_read_b64_tr_b16 v[126:127], v208 offset:3328
	ds_read_b64_tr_b16 v[128:129], v209 offset:12288
	ds_read_b64_tr_b16 v[130:131], v110 offset:12288
	s_waitcnt lgkmcnt(8)
	v_mfma_f32_32x32x16_bf16 v[76:91], v[156:159], v[160:163], v[76:91]
	ds_read_b64_tr_b16 v[132:133], v208 offset:4096
	ds_read_b64_tr_b16 v[134:135], v208 offset:4352
	ds_read_b64_tr_b16 v[136:137], v209 offset:16384
	ds_read_b64_tr_b16 v[138:139], v110 offset:16384
	s_waitcnt lgkmcnt(8)
	v_mfma_f32_32x32x16_bf16 v[76:91], v[116:119], v[120:123], v[76:91]
	ds_read_b64_tr_b16 v[140:141], v208 offset:5120
	ds_read_b64_tr_b16 v[142:143], v208 offset:5376
	ds_read_b64_tr_b16 v[144:145], v209 offset:20480
	ds_read_b64_tr_b16 v[146:147], v110 offset:20480
	s_waitcnt lgkmcnt(8)
	v_mfma_f32_32x32x16_bf16 v[76:91], v[124:127], v[128:131], v[76:91]
	ds_read_b64_tr_b16 v[148:149], v208 offset:6144
	ds_read_b64_tr_b16 v[150:151], v208 offset:6400
	ds_read_b64_tr_b16 v[152:153], v209 offset:24576
	ds_read_b64_tr_b16 v[154:155], v110 offset:24576
	s_waitcnt lgkmcnt(8)
	v_mfma_f32_32x32x16_bf16 v[76:91], v[132:135], v[136:139], v[76:91]
	ds_read_b64_tr_b16 v[156:157], v208 offset:7168
	ds_read_b64_tr_b16 v[158:159], v208 offset:7424
	ds_read_b64_tr_b16 v[160:161], v209 offset:28672
	ds_read_b64_tr_b16 v[162:163], v110 offset:28672
	s_waitcnt lgkmcnt(8)
	v_mfma_f32_32x32x16_bf16 v[76:91], v[140:143], v[144:147], v[76:91]
	s_waitcnt lgkmcnt(4)
	v_mfma_f32_32x32x16_bf16 v[76:91], v[148:151], v[152:155], v[76:91]
	s_waitcnt lgkmcnt(0)
	v_mfma_f32_32x32x16_bf16 v[76:91], v[156:159], v[160:163], v[76:91]
.Lm_noy_27:
	s_cmp_lt_u32 s50, 63
	s_cbranch_scc0 .Lm_now_28
	s_cmp_lt_u32 s3, 4
	s_cbranch_scc0 .Lm_whi_35
	s_waitcnt vmcnt(8)
	ds_write_b128 v169, v[56:59] offset:0
	ds_write_b128 v169, v[40:43] offset:34816
	ds_write_b128 v169, v[60:63] offset:8704
	ds_write_b128 v169, v[44:47] offset:43520
	ds_write_b128 v169, v[64:67] offset:17408
	ds_write_b128 v169, v[48:51] offset:52224
	ds_write_b128 v169, v[68:71] offset:26112
	ds_write_b128 v169, v[52:55] offset:60928
	s_branch .Lm_now_28
.Lm_whi_35:
	s_cmp_eq_u32 s3, 7
	s_cbranch_scc1 .Lm_wv7_33
	s_waitcnt vmcnt(10)
	s_branch .Lm_wvj_34
.Lm_wv7_33:
	s_waitcnt vmcnt(14)
.Lm_wvj_34:
	ds_read_b32 v116, v172 offset:2048
	ds_read_b32 v117, v171 offset:2048
	ds_read_b32 v118, v171 offset:2560
	ds_read_b32 v152, v171 offset:2304
	ds_read_b32 v153, v171 offset:2816
	ds_write_b128 v169, v[56:59] offset:0
	ds_write_b128 v169, v[40:43] offset:34816
	ds_write_b128 v169, v[60:63] offset:8704
	ds_write_b128 v169, v[44:47] offset:43520
	ds_write_b128 v169, v[64:67] offset:17408
	ds_write_b128 v169, v[48:51] offset:52224
	ds_write_b128 v169, v[68:71] offset:26112
	ds_write_b128 v169, v[52:55] offset:60928
	v_lshlrev_b32_e32 v120, 16, v72
	v_and_b32_e32 v121, 0xffff0000, v72
	v_lshlrev_b32_e32 v122, 16, v73
	v_and_b32_e32 v123, 0xffff0000, v73
	v_lshlrev_b32_e32 v124, 16, v74
	v_and_b32_e32 v125, 0xffff0000, v74
	v_lshlrev_b32_e32 v126, 16, v75
	v_and_b32_e32 v127, 0xffff0000, v75
	s_waitcnt lgkmcnt(8)
	v_sub_f32_e32 v119, v116, v117
	v_exp_f32_e32 v119, v119
	v_mul_f32_e32 v128, v118, v120
	v_mul_f32_e32 v129, v118, v121
	v_mul_f32_e32 v130, v118, v122
	v_mul_f32_e32 v131, v118, v123
	v_mul_f32_e32 v132, v118, v124
	v_mul_f32_e32 v133, v118, v125
	v_mul_f32_e32 v134, v118, v126
	v_mul_f32_e32 v135, v118, v127
	v_mul_f32_e32 v119, v118, v119
	v_cvt_pk_bf16_f32 v144, v128, v129
	v_cvt_pk_bf16_f32 v145, v130, v131
	v_cvt_pk_bf16_f32 v146, v132, v133
	v_cvt_pk_bf16_f32 v147, v134, v135
	v_mul_f32_e32 v136, v119, v120
	v_mul_f32_e32 v137, v119, v121
	v_mul_f32_e32 v138, v119, v122
	v_mul_f32_e32 v139, v119, v123
	v_mul_f32_e32 v140, v119, v124
	v_mul_f32_e32 v141, v119, v125
	v_mul_f32_e32 v142, v119, v126
	v_mul_f32_e32 v143, v119, v127
	v_cvt_pk_bf16_f32 v148, v136, v137
	v_cvt_pk_bf16_f32 v149, v138, v139
	v_cvt_pk_bf16_f32 v150, v140, v141
	v_cvt_pk_bf16_f32 v151, v142, v143
	ds_write_b128 v170, v[144:147] offset:43008
	ds_write_b128 v170, v[148:151] offset:10240
	v_lshlrev_b32_e32 v120, 16, v208
	v_and_b32_e32 v121, 0xffff0000, v208
	v_lshlrev_b32_e32 v122, 16, v209
	v_and_b32_e32 v123, 0xffff0000, v209
	v_lshlrev_b32_e32 v124, 16, v210
	v_and_b32_e32 v125, 0xffff0000, v210
	v_lshlrev_b32_e32 v126, 16, v211
	v_and_b32_e32 v127, 0xffff0000, v211
	v_sub_f32_e32 v119, v116, v152
	v_exp_f32_e32 v119, v119
	v_mul_f32_e32 v128, v153, v120
	v_mul_f32_e32 v129, v153, v121
	v_mul_f32_e32 v130, v153, v122
	v_mul_f32_e32 v131, v153, v123
	v_mul_f32_e32 v132, v153, v124
	v_mul_f32_e32 v133, v153, v125
	v_mul_f32_e32 v134, v153, v126
	v_mul_f32_e32 v135, v153, v127
	v_mul_f32_e32 v119, v153, v119
	v_cvt_pk_bf16_f32 v144, v128, v129
	v_cvt_pk_bf16_f32 v145, v130, v131
	v_cvt_pk_bf16_f32 v146, v132, v133
	v_cvt_pk_bf16_f32 v147, v134, v135
	v_mul_f32_e32 v136, v119, v120
	v_mul_f32_e32 v137, v119, v121
	v_mul_f32_e32 v138, v119, v122
	v_mul_f32_e32 v139, v119, v123
	v_mul_f32_e32 v140, v119, v124
	v_mul_f32_e32 v141, v119, v125
	v_mul_f32_e32 v142, v119, v126
	v_mul_f32_e32 v143, v119, v127
	v_cvt_pk_bf16_f32 v148, v136, v137
	v_cvt_pk_bf16_f32 v149, v138, v139
	v_cvt_pk_bf16_f32 v150, v140, v141
	v_cvt_pk_bf16_f32 v151, v142, v143
	ds_write_b128 v170, v[144:147] offset:47104
	ds_write_b128 v170, v[148:151] offset:14336

.Lm_noy2_31:
	s_add_u32 s44, s44, s49
	s_addc_u32 s45, s45, s55
	s_waitcnt lgkmcnt(0)
	s_barrier
	s_add_u32 s50, s50, 1
	s_cmp_lt_u32 s3, 3
	s_cbranch_scc0 .Lm_w3_41
	ds_read_b128 v[176:179], v216 offset:0
	ds_read_b128 v[116:119], v217 offset:34816
	ds_read_b128 v[180:183], v216 offset:32
	ds_read_b128 v[120:123], v217 offset:34848
	ds_read_b128 v[184:187], v216 offset:64
	ds_read_b128 v[124:127], v217 offset:34880
	ds_read_b128 v[188:191], v216 offset:96
	ds_read_b128 v[128:131], v217 offset:34912
	s_waitcnt lgkmcnt(6)
	v_mfma_f32_32x32x16_bf16 v[76:91], v[176:179], v[116:119], 0
	ds_read_b128 v[192:195], v216 offset:128
	ds_read_b128 v[116:119], v217 offset:34944
	global_load_dwordx4 v[40:43], v164, s[38:39]
	s_waitcnt lgkmcnt(6)
	v_mfma_f32_32x32x16_bf16 v[76:91], v[180:183], v[120:123], v[76:91]
	ds_read_b128 v[196:199], v216 offset:160
	ds_read_b128 v[120:123], v217 offset:34976
	global_load_dwordx4 v[56:59], v164, s[38:39] offset:256
	s_waitcnt lgkmcnt(6)
	v_mfma_f32_32x32x16_bf16 v[76:91], v[184:187], v[124:127], v[76:91]
	ds_read_b128 v[200:203], v216 offset:192
	ds_read_b128 v[124:127], v217 offset:35008
	global_load_dwordx4 v[44:47], v165, s[38:39]
	s_waitcnt lgkmcnt(6)
	v_mfma_f32_32x32x16_bf16 v[76:91], v[188:191], v[128:131], v[76:91]
	ds_read_b128 v[204:207], v216 offset:224
	ds_read_b128 v[128:131], v217 offset:35040
	global_load_dwordx4 v[60:63], v165, s[38:39] offset:256
	s_waitcnt lgkmcnt(6)
	v_mfma_f32_32x32x16_bf16 v[76:91], v[192:195], v[116:119], v[76:91]
	ds_read_b128 v[116:119], v217 offset:43520
	global_load_dwordx4 v[48:51], v166, s[38:39]
	ds_read_b128 v[234:237], v222 offset:2048
	ds_read_b128 v[238:241], v222 offset:2080
	ds_read_b128 v[242:245], v222 offset:2112
	ds_read_b128 v[246:249], v222 offset:2144
	ds_read_b32 v250, v223 offset:2048
	ds_read_b32 v251, v223 offset:2176
	s_waitcnt lgkmcnt(11)
	v_mfma_f32_32x32x16_bf16 v[76:91], v[196:199], v[120:123], v[76:91]
	ds_read_b128 v[120:123], v217 offset:43552
	global_load_dwordx4 v[64:67], v166, s[38:39] offset:256
	s_waitcnt lgkmcnt(10)
	v_mfma_f32_32x32x16_bf16 v[76:91], v[200:203], v[124:127], v[76:91]
	ds_read_b128 v[124:127], v217 offset:43584
	global_load_dwordx4 v[52:55], v167, s[38:39]
	s_waitcnt lgkmcnt(9)
	v_mfma_f32_32x32x16_bf16 v[76:91], v[204:207], v[128:131], v[76:91]
	ds_read_b128 v[128:131], v217 offset:43616
	global_load_dwordx4 v[68:71], v167, s[38:39] offset:256
	s_waitcnt lgkmcnt(3)
	s_cmp_eq_u32 s53, 0
	s_cbranch_scc0 .Lm_t0diag_43
	v_mfma_f32_32x32x16_bf16 v[92:107], v[176:179], v[116:119], 0
	ds_read_b128 v[116:119], v217 offset:43648
	v_sub_f32_e32 v132, v234, v250
	v_sub_f32_e32 v133, v235, v250
	v_sub_f32_e32 v134, v236, v250
	v_sub_f32_e32 v135, v237, v250
	v_sub_f32_e32 v136, v238, v250
	v_sub_f32_e32 v137, v239, v250
	v_sub_f32_e32 v138, v240, v250
	s_waitcnt lgkmcnt(3)
	v_mfma_f32_32x32x16_bf16 v[92:107], v[180:183], v[120:123], v[92:107]
	ds_read_b128 v[120:123], v217 offset:43680
	v_sub_f32_e32 v139, v241, v250
	v_sub_f32_e32 v140, v242, v250
	v_sub_f32_e32 v141, v243, v250
	v_sub_f32_e32 v142, v244, v250
	v_sub_f32_e32 v143, v245, v250
	v_sub_f32_e32 v144, v246, v250
	v_sub_f32_e32 v145, v247, v250
	s_waitcnt lgkmcnt(3)
	v_mfma_f32_32x32x16_bf16 v[92:107], v[184:187], v[124:127], v[92:107]
	ds_read_b128 v[124:127], v217 offset:43712
	v_sub_f32_e32 v146, v248, v250
	v_sub_f32_e32 v147, v249, v250
	v_exp_f32_e32 v132, v132
	v_exp_f32_e32 v133, v133
	v_exp_f32_e32 v134, v134
	v_exp_f32_e32 v135, v135
	v_exp_f32_e32 v136, v136
	s_waitcnt lgkmcnt(3)
	v_mfma_f32_32x32x16_bf16 v[92:107], v[188:191], v[128:131], v[92:107]
	ds_read_b128 v[128:131], v217 offset:43744
	v_exp_f32_e32 v137, v137
	v_exp_f32_e32 v138, v138
	v_exp_f32_e32 v139, v139
	v_exp_f32_e32 v140, v140
	v_exp_f32_e32 v141, v141
	v_exp_f32_e32 v142, v142
	v_exp_f32_e32 v143, v143
	s_waitcnt lgkmcnt(3)
	v_mfma_f32_32x32x16_bf16 v[92:107], v[192:195], v[116:119], v[92:107]
	v_exp_f32_e32 v144, v144
	v_exp_f32_e32 v145, v145
	v_exp_f32_e32 v146, v146
	v_exp_f32_e32 v147, v147
	v_mul_f32_e32 v76, v76, v132
	v_mul_f32_e32 v77, v77, v133
	v_mul_f32_e32 v78, v78, v134
	s_waitcnt lgkmcnt(2)
	v_mfma_f32_32x32x16_bf16 v[92:107], v[196:199], v[120:123], v[92:107]
	v_mul_f32_e32 v79, v79, v135
	v_mul_f32_e32 v80, v80, v136
	v_mul_f32_e32 v81, v81, v137
	v_mul_f32_e32 v82, v82, v138
	v_mul_f32_e32 v83, v83, v139
	v_mul_f32_e32 v84, v84, v140
	v_mul_f32_e32 v85, v85, v141
	s_waitcnt lgkmcnt(1)
	v_mfma_f32_32x32x16_bf16 v[92:107], v[200:203], v[124:127], v[92:107]
	v_mul_f32_e32 v86, v86, v142
	v_mul_f32_e32 v87, v87, v143
	v_mul_f32_e32 v88, v88, v144
	v_mul_f32_e32 v89, v89, v145
	v_mul_f32_e32 v90, v90, v146
	v_mul_f32_e32 v91, v91, v147
	v_cvt_pk_bf16_f32 v148, v76, v77
	s_waitcnt lgkmcnt(0)
	v_mfma_f32_32x32x16_bf16 v[92:107], v[204:207], v[128:131], v[92:107]
	v_cvt_pk_bf16_f32 v149, v78, v79
	v_cvt_pk_bf16_f32 v150, v80, v81
	v_cvt_pk_bf16_f32 v151, v82, v83
	v_cvt_pk_bf16_f32 v152, v84, v85
	v_cvt_pk_bf16_f32 v153, v86, v87
	v_cvt_pk_bf16_f32 v154, v88, v89
	v_cvt_pk_bf16_f32 v155, v90, v91
	s_branch .Lm_t0join_44

.Lm_w3_41:
	s_cmp_eq_u32 s3, 3
	s_cbranch_scc0 .Lm_w456_42
	ds_read_b128 v[116:119], v216 offset:0
	ds_read_b128 v[120:123], v217 offset:34816
	ds_read_b128 v[128:131], v216 offset:32
	ds_read_b128 v[132:135], v217 offset:34848
	ds_read_b128 v[140:143], v216 offset:64
	ds_read_b128 v[144:147], v217 offset:34880
	ds_read_b128 v[152:155], v216 offset:96
	ds_read_b128 v[156:159], v217 offset:34912
	s_waitcnt lgkmcnt(6)
	v_mfma_f32_32x32x16_bf16 v[76:91], v[116:119], v[120:123], 0
	ds_read_b128 v[116:119], v216 offset:128
	ds_read_b128 v[120:123], v217 offset:34944
	global_load_dwordx4 v[40:43], v164, s[38:39]
	s_waitcnt lgkmcnt(6)
	v_mfma_f32_32x32x16_bf16 v[76:91], v[128:131], v[132:135], v[76:91]
	ds_read_b128 v[128:131], v216 offset:160
	ds_read_b128 v[132:135], v217 offset:34976
	global_load_dwordx4 v[56:59], v164, s[38:39] offset:256
	s_waitcnt lgkmcnt(6)
	v_mfma_f32_32x32x16_bf16 v[76:91], v[140:143], v[144:147], v[76:91]
	ds_read_b128 v[140:143], v216 offset:192
	ds_read_b128 v[144:147], v217 offset:35008
	global_load_dwordx4 v[44:47], v165, s[38:39]
	s_waitcnt lgkmcnt(6)
	v_mfma_f32_32x32x16_bf16 v[76:91], v[152:155], v[156:159], v[76:91]
	ds_read_b128 v[152:155], v216 offset:224
	ds_read_b128 v[156:159], v217 offset:35040
	global_load_dwordx4 v[60:63], v165, s[38:39] offset:256
	s_waitcnt lgkmcnt(6)
	v_mfma_f32_32x32x16_bf16 v[76:91], v[116:119], v[120:123], v[76:91]
	global_load_dwordx4 v[48:51], v166, s[38:39]
	ds_read_b128 v[234:237], v222 offset:2048
	ds_read_b128 v[238:241], v222 offset:2080
	ds_read_b128 v[242:245], v222 offset:2112
	ds_read_b128 v[246:249], v222 offset:2144
	ds_read_b32 v250, v223 offset:2048
	s_waitcnt lgkmcnt(9)
	v_mfma_f32_32x32x16_bf16 v[76:91], v[128:131], v[132:135], v[76:91]
	global_load_dwordx4 v[64:67], v166, s[38:39] offset:256
	s_waitcnt lgkmcnt(7)
	v_mfma_f32_32x32x16_bf16 v[76:91], v[140:143], v[144:147], v[76:91]
	global_load_dwordx4 v[52:55], v167, s[38:39]
	s_waitcnt lgkmcnt(5)
	v_mfma_f32_32x32x16_bf16 v[76:91], v[152:155], v[156:159], v[76:91]
	global_load_dwordx4 v[68:71], v167, s[38:39] offset:256
	s_add_u32 s38, s38, s46
	s_addc_u32 s39, s39, s55
	s_add_u32 s40, s40, s47
	s_addc_u32 s41, s41, s55
	ds_read_b128 v[176:179], v173 offset:0
	ds_read_b128 v[180:183], v173 offset:32
	ds_read_b128 v[184:187], v173 offset:64
	ds_read_b128 v[188:191], v173 offset:96
	ds_read_b128 v[192:195], v173 offset:128
	ds_read_b128 v[196:199], v173 offset:160
	ds_read_b128 v[200:203], v173 offset:192
	ds_read_b128 v[204:207], v173 offset:224
	ds_read_b32 v2, v211 offset:2048
	s_waitcnt lgkmcnt(9)
	v_sub_f32_e32 v116, v234, v250
	v_sub_f32_e32 v117, v235, v250
	v_sub_f32_e32 v118, v236, v250
	v_sub_f32_e32 v119, v237, v250
	v_sub_f32_e32 v120, v238, v250
	v_sub_f32_e32 v121, v239, v250
	v_sub_f32_e32 v122, v240, v250
	v_sub_f32_e32 v123, v241, v250
	v_sub_f32_e32 v124, v242, v250
	v_sub_f32_e32 v125, v243, v250
	v_sub_f32_e32 v126, v244, v250
	v_sub_f32_e32 v127, v245, v250
	v_sub_f32_e32 v128, v246, v250
	v_sub_f32_e32 v129, v247, v250
	v_sub_f32_e32 v130, v248, v250
	v_sub_f32_e32 v131, v249, v250
	v_exp_f32_e32 v116, v116
	v_exp_f32_e32 v117, v117
	v_exp_f32_e32 v118, v118
	v_exp_f32_e32 v119, v119
	v_exp_f32_e32 v120, v120
	v_exp_f32_e32 v121, v121
	v_exp_f32_e32 v122, v122
	v_exp_f32_e32 v123, v123
	v_exp_f32_e32 v124, v124
	v_exp_f32_e32 v125, v125
	v_exp_f32_e32 v126, v126
	v_exp_f32_e32 v127, v127
	v_exp_f32_e32 v128, v128
	v_exp_f32_e32 v129, v129
	v_exp_f32_e32 v130, v130
	v_exp_f32_e32 v131, v131
	v_mul_f32_e32 v76, v76, v116
	v_mul_f32_e32 v77, v77, v117
	v_mul_f32_e32 v78, v78, v118
	v_mul_f32_e32 v79, v79, v119
	v_mul_f32_e32 v80, v80, v120
	v_mul_f32_e32 v81, v81, v121
	v_mul_f32_e32 v82, v82, v122
	v_mul_f32_e32 v83, v83, v123
	v_mul_f32_e32 v84, v84, v124
	v_mul_f32_e32 v85, v85, v125
	v_mul_f32_e32 v86, v86, v126
	v_mul_f32_e32 v87, v87, v127
	v_mul_f32_e32 v88, v88, v128
	v_mul_f32_e32 v89, v89, v129
	v_mul_f32_e32 v90, v90, v130
	v_mul_f32_e32 v91, v91, v131
	s_cmp_eq_u32 s53, 0
	s_cbranch_scc1 .Lm_nodiag_47
	v_cndmask_b32_e64 v76, 0, v76, s[64:65]
	v_cndmask_b32_e64 v77, 0, v77, s[66:67]
	v_cndmask_b32_e64 v78, 0, v78, s[68:69]
	v_cndmask_b32_e64 v79, 0, v79, s[70:71]
	v_cndmask_b32_e64 v80, 0, v80, s[72:73]
	v_cndmask_b32_e64 v81, 0, v81, s[74:75]
	v_cndmask_b32_e64 v82, 0, v82, s[76:77]
	v_cndmask_b32_e64 v83, 0, v83, s[78:79]
	v_cndmask_b32_e64 v84, 0, v84, s[80:81]
	v_cndmask_b32_e64 v85, 0, v85, s[82:83]
	v_cndmask_b32_e64 v86, 0, v86, s[84:85]
	v_cndmask_b32_e64 v87, 0, v87, s[86:87]
	v_cndmask_b32_e64 v88, 0, v88, s[88:89]
	v_cndmask_b32_e64 v89, 0, v89, s[90:91]
	v_cndmask_b32_e64 v90, 0, v90, s[92:93]
	v_cndmask_b32_e64 v91, 0, v91, s[94:95]

.Lm_w456_42:
	s_cmp_lt_u32 s3, 7
	s_cbranch_scc0 .Lm_g0_37
	ds_read_b128 v[116:119], v216 offset:0
	ds_read_b128 v[120:123], v217 offset:34816
	ds_read_b128 v[128:131], v216 offset:32
	ds_read_b128 v[132:135], v217 offset:34848
	ds_read_b128 v[140:143], v216 offset:64
	ds_read_b128 v[144:147], v217 offset:34880
	ds_read_b128 v[152:155], v216 offset:96
	ds_read_b128 v[156:159], v217 offset:34912
	s_waitcnt lgkmcnt(6)
	v_mfma_f32_32x32x16_bf16 v[76:91], v[116:119], v[120:123], 0
	ds_read_b128 v[116:119], v216 offset:128
	ds_read_b128 v[120:123], v217 offset:34944
	global_load_dwordx4 v[40:43], v164, s[38:39]
	s_waitcnt lgkmcnt(6)
	v_mfma_f32_32x32x16_bf16 v[76:91], v[128:131], v[132:135], v[76:91]
	ds_read_b128 v[128:131], v216 offset:160
	ds_read_b128 v[132:135], v217 offset:34976
	global_load_dwordx4 v[56:59], v164, s[38:39] offset:256
	s_waitcnt lgkmcnt(6)
	v_mfma_f32_32x32x16_bf16 v[76:91], v[140:143], v[144:147], v[76:91]
	ds_read_b128 v[140:143], v216 offset:192
	ds_read_b128 v[144:147], v217 offset:35008
	global_load_dwordx4 v[44:47], v165, s[38:39]
	s_waitcnt lgkmcnt(6)
	v_mfma_f32_32x32x16_bf16 v[76:91], v[152:155], v[156:159], v[76:91]
	ds_read_b128 v[152:155], v216 offset:224
	ds_read_b128 v[156:159], v217 offset:35040
	global_load_dwordx4 v[60:63], v165, s[38:39] offset:256
	s_waitcnt lgkmcnt(6)
	v_mfma_f32_32x32x16_bf16 v[76:91], v[116:119], v[120:123], v[76:91]
	global_load_dwordx4 v[48:51], v166, s[38:39]
	ds_read_b128 v[234:237], v222 offset:2048
	ds_read_b128 v[238:241], v222 offset:2080
	ds_read_b128 v[242:245], v222 offset:2112
	ds_read_b128 v[246:249], v222 offset:2144
	ds_read_b32 v250, v223 offset:2048
	s_waitcnt lgkmcnt(9)
	v_mfma_f32_32x32x16_bf16 v[76:91], v[128:131], v[132:135], v[76:91]
	global_load_dwordx4 v[64:67], v166, s[38:39] offset:256
	s_waitcnt lgkmcnt(7)
	v_mfma_f32_32x32x16_bf16 v[76:91], v[140:143], v[144:147], v[76:91]
	global_load_dwordx4 v[52:55], v167, s[38:39]
	s_waitcnt lgkmcnt(5)
	v_mfma_f32_32x32x16_bf16 v[76:91], v[152:155], v[156:159], v[76:91]
	global_load_dwordx4 v[68:71], v167, s[38:39] offset:256
	global_load_dwordx4 v[72:75], v168, s[40:41]
	global_load_dwordx4 v[208:211], v202, s[40:41]
	s_add_u32 s38, s38, s46
	s_addc_u32 s39, s39, s55
	s_add_u32 s40, s40, s47
	s_addc_u32 s41, s41, s55
	s_waitcnt lgkmcnt(0)
	ds_read_b32 v1, v172 offset:2048
	ds_read_b64_tr_b16 v[116:117], v193 offset:0
	ds_read_b64_tr_b16 v[118:119], v193 offset:1088
	ds_read_b64_tr_b16 v[120:121], v192 offset:0
	ds_read_b64_tr_b16 v[122:123], v192 offset:256
	ds_read_b64_tr_b16 v[124:125], v193 offset:4352
	ds_read_b64_tr_b16 v[126:127], v193 offset:5440
	ds_read_b64_tr_b16 v[128:129], v192 offset:1024
	ds_read_b64_tr_b16 v[130:131], v192 offset:1280
	ds_read_b64_tr_b16 v[132:133], v193 offset:8704
	ds_read_b64_tr_b16 v[134:135], v193 offset:9792
	ds_read_b64_tr_b16 v[136:137], v192 offset:2048
	ds_read_b64_tr_b16 v[138:139], v192 offset:2304
	s_waitcnt lgkmcnt(12)
	v_exp_f32_e32 v1, v1
	s_nop 0
	v_mul_f32_e32 v176, v176, v1
	v_mul_f32_e32 v177, v177, v1
	v_mul_f32_e32 v178, v178, v1
	v_mul_f32_e32 v179, v179, v1
	v_mul_f32_e32 v180, v180, v1
	v_mul_f32_e32 v181, v181, v1
	v_mul_f32_e32 v182, v182, v1
	v_mul_f32_e32 v183, v183, v1
	v_mul_f32_e32 v184, v184, v1
	v_mul_f32_e32 v185, v185, v1
	v_mul_f32_e32 v186, v186, v1
	v_mul_f32_e32 v187, v187, v1
	v_mul_f32_e32 v188, v188, v1
	v_mul_f32_e32 v189, v189, v1
	v_mul_f32_e32 v190, v190, v1
	v_mul_f32_e32 v191, v191, v1
	s_nop 1
	s_cmp_eq_u32 s53, 0
	s_cbranch_scc0 .Lm_sdiag_48
	s_waitcnt lgkmcnt(8)
	v_mfma_f32_32x32x16_bf16 v[176:191], v[116:119], v[120:123], v[176:191]
	ds_read_b64_tr_b16 v[116:117], v193 offset:13056
	ds_read_b64_tr_b16 v[118:119], v193 offset:14144
	ds_read_b64_tr_b16 v[120:121], v192 offset:3072
	ds_read_b64_tr_b16 v[122:123], v192 offset:3328
	v_sub_f32_e32 v140, v234, v250
	v_sub_f32_e32 v141, v235, v250
	v_sub_f32_e32 v142, v236, v250
	v_sub_f32_e32 v143, v237, v250
	v_sub_f32_e32 v144, v238, v250
	v_sub_f32_e32 v145, v239, v250
	v_sub_f32_e32 v146, v240, v250
	s_waitcnt lgkmcnt(8)
	v_mfma_f32_32x32x16_bf16 v[176:191], v[124:127], v[128:131], v[176:191]
	ds_read_b64_tr_b16 v[124:125], v193 offset:17408
	ds_read_b64_tr_b16 v[126:127], v193 offset:18496
	ds_read_b64_tr_b16 v[128:129], v192 offset:4096
	ds_read_b64_tr_b16 v[130:131], v192 offset:4352
	v_sub_f32_e32 v147, v241, v250
	v_sub_f32_e32 v148, v242, v250
	v_sub_f32_e32 v149, v243, v250
	v_sub_f32_e32 v150, v244, v250
	v_sub_f32_e32 v151, v245, v250
	v_sub_f32_e32 v152, v246, v250
	v_sub_f32_e32 v153, v247, v250
	s_waitcnt lgkmcnt(8)
	v_mfma_f32_32x32x16_bf16 v[176:191], v[132:135], v[136:139], v[176:191]
	ds_read_b64_tr_b16 v[132:133], v193 offset:21760
	ds_read_b64_tr_b16 v[134:135], v193 offset:22848
	ds_read_b64_tr_b16 v[136:137], v192 offset:5120
	ds_read_b64_tr_b16 v[138:139], v192 offset:5376
	v_sub_f32_e32 v154, v248, v250
	v_sub_f32_e32 v155, v249, v250
	v_exp_f32_e32 v140, v140
	v_exp_f32_e32 v141, v141
	v_exp_f32_e32 v142, v142
	v_exp_f32_e32 v143, v143
	v_exp_f32_e32 v144, v144
	s_waitcnt lgkmcnt(8)
	v_mfma_f32_32x32x16_bf16 v[176:191], v[116:119], v[120:123], v[176:191]
	ds_read_b64_tr_b16 v[116:117], v193 offset:26112
	ds_read_b64_tr_b16 v[118:119], v193 offset:27200
	ds_read_b64_tr_b16 v[120:121], v192 offset:6144
	ds_read_b64_tr_b16 v[122:123], v192 offset:6400
	v_exp_f32_e32 v145, v145
	v_exp_f32_e32 v146, v146
	v_exp_f32_e32 v147, v147
	v_exp_f32_e32 v148, v148
	v_exp_f32_e32 v149, v149
	v_exp_f32_e32 v150, v150
	v_exp_f32_e32 v151, v151
	s_waitcnt lgkmcnt(8)
	v_mfma_f32_32x32x16_bf16 v[176:191], v[124:127], v[128:131], v[176:191]
	ds_read_b64_tr_b16 v[124:125], v193 offset:30464
	ds_read_b64_tr_b16 v[126:127], v193 offset:31552
	ds_read_b64_tr_b16 v[128:129], v192 offset:7168
	ds_read_b64_tr_b16 v[130:131], v192 offset:7424
	v_exp_f32_e32 v152, v152
	v_exp_f32_e32 v153, v153
	v_exp_f32_e32 v154, v154
	v_exp_f32_e32 v155, v155
	v_mul_f32_e32 v76, v76, v140
	v_mul_f32_e32 v77, v77, v141
	v_mul_f32_e32 v78, v78, v142
	s_waitcnt lgkmcnt(8)
	v_mfma_f32_32x32x16_bf16 v[176:191], v[132:135], v[136:139], v[176:191]
	v_mul_f32_e32 v79, v79, v143
	v_mul_f32_e32 v80, v80, v144
	v_mul_f32_e32 v81, v81, v145
	v_mul_f32_e32 v82, v82, v146
	v_mul_f32_e32 v83, v83, v147
	v_mul_f32_e32 v84, v84, v148
	v_mul_f32_e32 v85, v85, v149
	s_waitcnt lgkmcnt(4)
	v_mfma_f32_32x32x16_bf16 v[176:191], v[116:119], v[120:123], v[176:191]
	v_mul_f32_e32 v86, v86, v150
	v_mul_f32_e32 v87, v87, v151
	v_mul_f32_e32 v88, v88, v152
	v_mul_f32_e32 v89, v89, v153
	v_mul_f32_e32 v90, v90, v154
	v_mul_f32_e32 v91, v91, v155
	v_cvt_pk_bf16_f32 v156, v76, v77
	s_waitcnt lgkmcnt(0)
	v_mfma_f32_32x32x16_bf16 v[176:191], v[124:127], v[128:131], v[176:191]
	v_cvt_pk_bf16_f32 v157, v78, v79
	v_cvt_pk_bf16_f32 v158, v80, v81
	v_cvt_pk_bf16_f32 v159, v82, v83
	v_cvt_pk_bf16_f32 v160, v84, v85
	v_cvt_pk_bf16_f32 v161, v86, v87
	v_cvt_pk_bf16_f32 v162, v88, v89
	v_cvt_pk_bf16_f32 v163, v90, v91
	s_branch .Lm_sjoin_49

.Lm_g0_37:
	ds_read_b32 v1, v172 offset:2048
	ds_read_b64_tr_b16 v[116:117], v193 offset:0
	ds_read_b64_tr_b16 v[118:119], v193 offset:1088
	ds_read_b64_tr_b16 v[120:121], v192 offset:0
	ds_read_b64_tr_b16 v[122:123], v192 offset:256
	ds_read_b64_tr_b16 v[124:125], v193 offset:4352
	ds_read_b64_tr_b16 v[126:127], v193 offset:5440
	ds_read_b64_tr_b16 v[128:129], v192 offset:1024
	ds_read_b64_tr_b16 v[130:131], v192 offset:1280
	ds_read_b64_tr_b16 v[132:133], v193 offset:8704
	ds_read_b64_tr_b16 v[134:135], v193 offset:9792
	ds_read_b64_tr_b16 v[136:137], v192 offset:2048
	ds_read_b64_tr_b16 v[138:139], v192 offset:2304
	s_waitcnt lgkmcnt(12)
	v_exp_f32_e32 v1, v1
	s_nop 0
	v_mul_f32_e32 v176, v176, v1
	v_mul_f32_e32 v177, v177, v1
	v_mul_f32_e32 v178, v178, v1
	v_mul_f32_e32 v179, v179, v1
	v_mul_f32_e32 v180, v180, v1
	v_mul_f32_e32 v181, v181, v1
	v_mul_f32_e32 v182, v182, v1
	v_mul_f32_e32 v183, v183, v1
	v_mul_f32_e32 v184, v184, v1
	v_mul_f32_e32 v185, v185, v1
	v_mul_f32_e32 v186, v186, v1
	v_mul_f32_e32 v187, v187, v1
	v_mul_f32_e32 v188, v188, v1
	v_mul_f32_e32 v189, v189, v1
	v_mul_f32_e32 v190, v190, v1
	v_mul_f32_e32 v191, v191, v1
	s_nop 1
	s_waitcnt lgkmcnt(8)
	v_mfma_f32_32x32x16_bf16 v[176:191], v[116:119], v[120:123], v[176:191]
	ds_read_b64_tr_b16 v[116:117], v193 offset:13056
	ds_read_b64_tr_b16 v[118:119], v193 offset:14144
	ds_read_b64_tr_b16 v[120:121], v192 offset:3072
	ds_read_b64_tr_b16 v[122:123], v192 offset:3328
	global_load_dwordx4 v[40:43], v164, s[38:39]
	s_waitcnt lgkmcnt(8)
	v_mfma_f32_32x32x16_bf16 v[176:191], v[124:127], v[128:131], v[176:191]
	ds_read_b64_tr_b16 v[124:125], v193 offset:17408
	ds_read_b64_tr_b16 v[126:127], v193 offset:18496
	ds_read_b64_tr_b16 v[128:129], v192 offset:4096
	ds_read_b64_tr_b16 v[130:131], v192 offset:4352
	global_load_dwordx4 v[56:59], v164, s[38:39] offset:256
	s_waitcnt lgkmcnt(8)
	v_mfma_f32_32x32x16_bf16 v[176:191], v[132:135], v[136:139], v[176:191]
	ds_read_b64_tr_b16 v[132:133], v193 offset:21760
	ds_read_b64_tr_b16 v[134:135], v193 offset:22848
	ds_read_b64_tr_b16 v[136:137], v192 offset:5120
	ds_read_b64_tr_b16 v[138:139], v192 offset:5376
	global_load_dwordx4 v[44:47], v165, s[38:39]
	s_waitcnt lgkmcnt(8)
	v_mfma_f32_32x32x16_bf16 v[176:191], v[116:119], v[120:123], v[176:191]
	ds_read_b64_tr_b16 v[116:117], v193 offset:26112
	ds_read_b64_tr_b16 v[118:119], v193 offset:27200
	ds_read_b64_tr_b16 v[120:121], v192 offset:6144
	ds_read_b64_tr_b16 v[122:123], v192 offset:6400
	global_load_dwordx4 v[60:63], v165, s[38:39] offset:256
	s_waitcnt lgkmcnt(8)
	v_mfma_f32_32x32x16_bf16 v[176:191], v[124:127], v[128:131], v[176:191]
	ds_read_b64_tr_b16 v[124:125], v193 offset:30464
	ds_read_b64_tr_b16 v[126:127], v193 offset:31552
	ds_read_b64_tr_b16 v[128:129], v192 offset:7168
	ds_read_b64_tr_b16 v[130:131], v192 offset:7424
	global_load_dwordx4 v[48:51], v166, s[38:39]
	s_waitcnt lgkmcnt(8)
	v_mfma_f32_32x32x16_bf16 v[176:191], v[132:135], v[136:139], v[176:191]
	global_load_dwordx4 v[64:67], v166, s[38:39] offset:256
	s_waitcnt lgkmcnt(4)
	v_mfma_f32_32x32x16_bf16 v[176:191], v[116:119], v[120:123], v[176:191]
	global_load_dwordx4 v[52:55], v167, s[38:39]
	s_waitcnt lgkmcnt(0)
	v_mfma_f32_32x32x16_bf16 v[176:191], v[124:127], v[128:131], v[176:191]
	global_load_dwordx4 v[68:71], v167, s[38:39] offset:256
	global_load_dwordx4 v[72:75], v168, s[40:41]
	global_load_dwordx4 v[208:211], v202, s[40:41]
	s_add_u32 s38, s38, s46
	s_addc_u32 s39, s39, s55
	s_add_u32 s40, s40, s47
	s_addc_u32 s41, s41, s55
	s_nop 7
	s_nop 3
	v_cvt_pk_bf16_f32 v140, v176, v177
	v_cvt_pk_bf16_f32 v141, v178, v179
	v_cvt_pk_bf16_f32 v142, v180, v181
	v_cvt_pk_bf16_f32 v143, v182, v183
	v_cvt_pk_bf16_f32 v144, v184, v185
	v_cvt_pk_bf16_f32 v145, v186, v187
	v_cvt_pk_bf16_f32 v146, v188, v189
	v_cvt_pk_bf16_f32 v147, v190, v191
	ds_write_b64 v194, v[140:141] offset:0
	ds_write_b64 v194, v[142:143] offset:16
	ds_write_b64 v194, v[144:145] offset:32
	ds_write_b64 v194, v[146:147] offset:48
	s_cmp_lt_u32 s50, 63
	s_cbranch_scc0 .Lm_noscan_50
	s_waitcnt vmcnt(10)
	v_mul_f32_e32 v116, s62, v204
	v_mul_f32_e32 v117, s62, v205
	v_add_f32_e32 v118, v116, v117
	s_nop 1
	v_add_f32_dpp v118, v118, v118 row_shr:1 row_mask:0xf bank_mask:0xf bound_ctrl:0
	s_nop 1
	v_add_f32_dpp v118, v118, v118 row_shr:2 row_mask:0xf bank_mask:0xf bound_ctrl:0
	s_nop 1
	v_add_f32_dpp v118, v118, v118 row_shr:4 row_mask:0xf bank_mask:0xf bound_ctrl:0
	s_nop 1
	v_add_f32_dpp v118, v118, v118 row_shr:8 row_mask:0xf bank_mask:0xf bound_ctrl:0
	s_nop 1
	v_add_f32_dpp v118, v118, v118 row_bcast:15 row_mask:0xa bank_mask:0xf
	s_nop 1
	v_add_f32_dpp v118, v118, v118 row_bcast:31 row_mask:0xc bank_mask:0xf
	s_nop 1
	v_readlane_b32 s97, v118, 63
	v_sub_f32_e32 v122, v118, v117
	v_mov_b32_e32 v123, v118
	s_nop 1
	s_cmp_eq_u32 s51, 0
	s_cbranch_scc1 .Lm_scanf_51
	v_sub_f32_e32 v122, s97, v122
	v_sub_f32_e32 v123, s97, v123
	v_fma_f32 v122, v204, s62, v122
	v_fma_f32 v123, v205, s62, v123

.Lm_noscan_50:
.Lm_adone_40:
	s_waitcnt lgkmcnt(0)
	s_barrier
	s_cmp_lt_u32 s3, 4
	s_cbranch_scc0 .Lm_noy_52
	ds_read_b128 v[116:119], v210 offset:8704
	ds_read_b128 v[120:123], v210 offset:8736
	ds_read_b128 v[124:127], v210 offset:8768
	ds_read_b128 v[128:131], v210 offset:8800
	ds_read_b128 v[132:135], v210 offset:8832
	ds_read_b128 v[136:139], v210 offset:8864
	ds_read_b128 v[140:143], v210 offset:8896
	ds_read_b128 v[144:147], v210 offset:8928
	ds_read_b64_tr_b16 v[148:149], v208 offset:43008
	ds_read_b64_tr_b16 v[150:151], v208 offset:43264
	ds_read_b64_tr_b16 v[152:153], v209 offset:0
	ds_read_b64_tr_b16 v[154:155], v110 offset:0
	s_waitcnt lgkmcnt(11)
	v_mfma_f32_32x32x16_bf16 v[92:107], v[116:119], v[176:179], 0
	s_waitcnt lgkmcnt(10)
	v_mfma_f32_32x32x16_bf16 v[92:107], v[120:123], v[180:183], v[92:107]
	ds_read_b64_tr_b16 v[156:157], v208 offset:44032
	ds_read_b64_tr_b16 v[158:159], v208 offset:44288
	ds_read_b64_tr_b16 v[160:161], v209 offset:4096
	ds_read_b64_tr_b16 v[162:163], v110 offset:4096
	s_waitcnt lgkmcnt(13)
	v_mfma_f32_32x32x16_bf16 v[92:107], v[124:127], v[184:187], v[92:107]
	s_waitcnt lgkmcnt(12)
	v_mfma_f32_32x32x16_bf16 v[92:107], v[128:131], v[188:191], v[92:107]
	s_waitcnt lgkmcnt(11)
	v_mfma_f32_32x32x16_bf16 v[92:107], v[132:135], v[192:195], v[92:107]
	ds_read_b64_tr_b16 v[116:117], v208 offset:45056
	ds_read_b64_tr_b16 v[118:119], v208 offset:45312
	ds_read_b64_tr_b16 v[120:121], v209 offset:8192
	ds_read_b64_tr_b16 v[122:123], v110 offset:8192
	s_waitcnt lgkmcnt(14)
	v_mfma_f32_32x32x16_bf16 v[92:107], v[136:139], v[196:199], v[92:107]
	s_waitcnt lgkmcnt(13)
	v_mfma_f32_32x32x16_bf16 v[92:107], v[140:143], v[200:203], v[92:107]
	s_waitcnt lgkmcnt(12)
	v_mfma_f32_32x32x16_bf16 v[92:107], v[144:147], v[204:207], v[92:107]
	s_waitcnt lgkmcnt(8)
	v_mfma_f32_32x32x16_bf16 v[76:91], v[148:151], v[152:155], 0
	ds_read_b64_tr_b16 v[124:125], v208 offset:46080
	ds_read_b64_tr_b16 v[126:127], v208 offset:46336
	ds_read_b64_tr_b16 v[128:129], v209 offset:12288
	ds_read_b64_tr_b16 v[130:131], v110 offset:12288
	s_waitcnt lgkmcnt(8)
	v_mfma_f32_32x32x16_bf16 v[76:91], v[156:159], v[160:163], v[76:91]
	ds_read_b64_tr_b16 v[132:133], v208 offset:47104
	ds_read_b64_tr_b16 v[134:135], v208 offset:47360
	ds_read_b64_tr_b16 v[136:137], v209 offset:16384
	ds_read_b64_tr_b16 v[138:139], v110 offset:16384
	s_waitcnt lgkmcnt(8)
	v_mfma_f32_32x32x16_bf16 v[76:91], v[116:119], v[120:123], v[76:91]
	ds_read_b64_tr_b16 v[140:141], v208 offset:48128
	ds_read_b64_tr_b16 v[142:143], v208 offset:48384
	ds_read_b64_tr_b16 v[144:145], v209 offset:20480
	ds_read_b64_tr_b16 v[146:147], v110 offset:20480
	s_waitcnt lgkmcnt(8)
	v_mfma_f32_32x32x16_bf16 v[76:91], v[124:127], v[128:131], v[76:91]
	ds_read_b64_tr_b16 v[148:149], v208 offset:49152
	ds_read_b64_tr_b16 v[150:151], v208 offset:49408
	ds_read_b64_tr_b16 v[152:153], v209 offset:24576
	ds_read_b64_tr_b16 v[154:155], v110 offset:24576
	s_waitcnt lgkmcnt(8)
	v_mfma_f32_32x32x16_bf16 v[76:91], v[132:135], v[136:139], v[76:91]
	ds_read_b64_tr_b16 v[156:157], v208 offset:50176
	ds_read_b64_tr_b16 v[158:159], v208 offset:50432
	ds_read_b64_tr_b16 v[160:161], v209 offset:28672
	ds_read_b64_tr_b16 v[162:163], v110 offset:28672
	s_waitcnt lgkmcnt(8)
	v_mfma_f32_32x32x16_bf16 v[76:91], v[140:143], v[144:147], v[76:91]
	s_waitcnt lgkmcnt(4)
	v_mfma_f32_32x32x16_bf16 v[76:91], v[148:151], v[152:155], v[76:91]
	s_waitcnt lgkmcnt(0)
	v_mfma_f32_32x32x16_bf16 v[76:91], v[156:159], v[160:163], v[76:91]
.Lm_noy_52:
	s_cmp_lt_u32 s50, 63
	s_cbranch_scc0 .Lm_now_53
	s_cmp_lt_u32 s3, 4
	s_cbranch_scc0 .Lm_whi_60
	s_waitcnt vmcnt(8)
	ds_write_b128 v169, v[20:23] offset:0
	ds_write_b128 v169, v[4:7] offset:34816
	ds_write_b128 v169, v[24:27] offset:8704
	ds_write_b128 v169, v[8:11] offset:43520
	ds_write_b128 v169, v[28:31] offset:17408
	ds_write_b128 v169, v[12:15] offset:52224
	ds_write_b128 v169, v[32:35] offset:26112
	ds_write_b128 v169, v[16:19] offset:60928
	s_branch .Lm_now_53

.Lm_wvj_59:
	ds_read_b32 v116, v172 offset:0
	ds_read_b32 v117, v171 offset:0
	ds_read_b32 v118, v171 offset:512
	ds_read_b32 v152, v171 offset:256
	ds_read_b32 v153, v171 offset:768
	ds_write_b128 v169, v[20:23] offset:0
	ds_write_b128 v169, v[4:7] offset:34816
	ds_write_b128 v169, v[24:27] offset:8704
	ds_write_b128 v169, v[8:11] offset:43520
	ds_write_b128 v169, v[28:31] offset:17408
	ds_write_b128 v169, v[12:15] offset:52224
	ds_write_b128 v169, v[32:35] offset:26112
	ds_write_b128 v169, v[16:19] offset:60928
	v_lshlrev_b32_e32 v120, 16, v36
	v_and_b32_e32 v121, 0xffff0000, v36
	v_lshlrev_b32_e32 v122, 16, v37
	v_and_b32_e32 v123, 0xffff0000, v37
	v_lshlrev_b32_e32 v124, 16, v38
	v_and_b32_e32 v125, 0xffff0000, v38
	v_lshlrev_b32_e32 v126, 16, v39
	v_and_b32_e32 v127, 0xffff0000, v39
	s_waitcnt lgkmcnt(8)
	v_sub_f32_e32 v119, v116, v117
	v_exp_f32_e32 v119, v119
	v_mul_f32_e32 v128, v118, v120
	v_mul_f32_e32 v129, v118, v121
	v_mul_f32_e32 v130, v118, v122
	v_mul_f32_e32 v131, v118, v123
	v_mul_f32_e32 v132, v118, v124
	v_mul_f32_e32 v133, v118, v125
	v_mul_f32_e32 v134, v118, v126
	v_mul_f32_e32 v135, v118, v127
	v_mul_f32_e32 v119, v118, v119
	v_cvt_pk_bf16_f32 v144, v128, v129
	v_cvt_pk_bf16_f32 v145, v130, v131
	v_cvt_pk_bf16_f32 v146, v132, v133
	v_cvt_pk_bf16_f32 v147, v134, v135
	v_mul_f32_e32 v136, v119, v120
	v_mul_f32_e32 v137, v119, v121
	v_mul_f32_e32 v138, v119, v122
	v_mul_f32_e32 v139, v119, v123
	v_mul_f32_e32 v140, v119, v124
	v_mul_f32_e32 v141, v119, v125
	v_mul_f32_e32 v142, v119, v126
	v_mul_f32_e32 v143, v119, v127
	v_cvt_pk_bf16_f32 v148, v136, v137
	v_cvt_pk_bf16_f32 v149, v138, v139
	v_cvt_pk_bf16_f32 v150, v140, v141
	v_cvt_pk_bf16_f32 v151, v142, v143
	ds_write_b128 v170, v[144:147] offset:0
	ds_write_b128 v170, v[148:151] offset:10240
	v_lshlrev_b32_e32 v120, 16, v198
	v_and_b32_e32 v121, 0xffff0000, v198
	v_lshlrev_b32_e32 v122, 16, v199
	v_and_b32_e32 v123, 0xffff0000, v199
	v_lshlrev_b32_e32 v124, 16, v200
	v_and_b32_e32 v125, 0xffff0000, v200
	v_lshlrev_b32_e32 v126, 16, v201
	v_and_b32_e32 v127, 0xffff0000, v201
	v_sub_f32_e32 v119, v116, v152
	v_exp_f32_e32 v119, v119
	v_mul_f32_e32 v128, v153, v120
	v_mul_f32_e32 v129, v153, v121
	v_mul_f32_e32 v130, v153, v122
	v_mul_f32_e32 v131, v153, v123
	v_mul_f32_e32 v132, v153, v124
	v_mul_f32_e32 v133, v153, v125
	v_mul_f32_e32 v134, v153, v126
	v_mul_f32_e32 v135, v153, v127
	v_mul_f32_e32 v119, v153, v119
	v_cvt_pk_bf16_f32 v144, v128, v129
	v_cvt_pk_bf16_f32 v145, v130, v131
	v_cvt_pk_bf16_f32 v146, v132, v133
	v_cvt_pk_bf16_f32 v147, v134, v135
	v_mul_f32_e32 v136, v119, v120
	v_mul_f32_e32 v137, v119, v121
	v_mul_f32_e32 v138, v119, v122
	v_mul_f32_e32 v139, v119, v123
	v_mul_f32_e32 v140, v119, v124
	v_mul_f32_e32 v141, v119, v125
	v_mul_f32_e32 v142, v119, v126
	v_mul_f32_e32 v143, v119, v127
	v_cvt_pk_bf16_f32 v148, v136, v137
	v_cvt_pk_bf16_f32 v149, v138, v139
	v_cvt_pk_bf16_f32 v150, v140, v141
	v_cvt_pk_bf16_f32 v151, v142, v143
	ds_write_b128 v170, v[144:147] offset:4096
	ds_write_b128 v170, v[148:151] offset:14336

.LBB0_333:
	s_bfe_u32 s24, s23, 0x60002
	s_lshl_b32 s10, s24, 7
	v_add_u32_e32 v1, s10, v182
	s_ashr_i32 s14, s23, 8
	v_max_i32_e32 v2, 0xffffffc0, v1
	s_ashr_i32 s15, s14, 31
	v_add_u32_e32 v2, 64, v2
	v_readlane_b32 s16, v254, 33
	s_lshl_b64 s[14:15], s[14:15], 13
	v_min_u32_e32 v2, 0x1fff, v2
	v_readlane_b32 s17, v254, 34
	v_or_b32_e32 v4, s14, v2
	s_movk_i32 s11, 0xc00
	v_mov_b64_e32 v[2:3], s[16:17]
	s_and_b32 s3, s23, 3
	v_mad_u64_u32 v[4:5], s[16:17], v4, s11, v[2:3]
	v_mad_i32_i24 v5, s15, v230, v5
	s_lshl_b32 s16, s3, 7
	s_mov_b32 s17, s12
	v_lshl_add_u64 v[4:5], v[4:5], 0, s[16:17]
	v_lshlrev_b32_e32 v50, 1, v168
	v_mov_b32_e32 v51, v0
	v_lshl_add_u64 v[4:5], v[4:5], 0, v[50:51]
	v_add_u32_e32 v63, s10, v169
	s_waitcnt lgkmcnt(0)
	s_barrier
	v_and_b32_e32 v197, 7, v175
	v_lshrrev_b32_e32 v198, 3, v175
	v_cmp_gt_u32_e64 s[16:17], 2, v197
	v_cmp_eq_u32_e64 s[26:27], 0, v197
	v_lshlrev_b32_e32 v3, 4, v197
	v_mov_b32_e32 v80, 0x90
	v_mad_u32_u24 v3, v198, v80, v3
	v_add_u32_e32 v200, 0xd800, v3
	v_lshlrev_b32_e32 v197, 4, v197
	v_add_u32_e32 v199, s10, v198
	v_add_u32_e32 v199, 0xffffff80, v199
	v_readlane_b32 s18, v254, 33
	v_readlane_b32 s19, v254, 34
	s_mul_i32 s11, s14, 0xc00
	s_add_u32 s18, s18, s11
	s_addc_u32 s19, s19, 0
	s_lshl_b32 s11, s3, 7
	s_add_u32 s18, s18, s11
	s_addc_u32 s19, s19, 0
	s_add_u32 vcc_lo, s36, 0x180000
	s_addc_u32 vcc_hi, s37, 0
	s_movk_i32 s11, 0xc00
	global_load_dwordx4 v[52:55], v[176:177], off
	global_load_dwordx4 v[56:59], v[176:177], off offset:16
	v_add_u32_e32 v198, 0, v199
	v_max_i32_e32 v198, 0, v198
	v_min_u32_e32 v198, 0x1fff, v198
	v_mul_lo_u32 v1, v198, s11
	v_add_u32_e32 v1, v1, v197
	v_lshlrev_b32_e32 v2, 6, v198
	global_load_dwordx4 v[4:7], v1, s[18:19] offset:2048
	global_load_dwordx4 v[8:11], v1, s[18:19] offset:2560
	s_mov_b64 exec, s[16:17]
	global_load_dwordx4 v[116:119], v2, vcc offset:0
	global_load_dwordx4 v[120:123], v2, vcc offset:16
	global_load_dwordx4 v[124:127], v2, vcc offset:32
	global_load_dwordx4 v[128:131], v2, vcc offset:48
	s_mov_b64 exec, -1
	v_add_u32_e32 v198, 64, v199
	v_max_i32_e32 v198, 0, v198
	v_min_u32_e32 v198, 0x1fff, v198
	v_mul_lo_u32 v1, v198, s11
	v_add_u32_e32 v1, v1, v197
	v_lshlrev_b32_e32 v2, 6, v198
	global_load_dwordx4 v[12:15], v1, s[18:19] offset:2048
	global_load_dwordx4 v[16:19], v1, s[18:19] offset:2560
	s_mov_b64 exec, s[16:17]
	global_load_dwordx4 v[132:135], v2, vcc offset:0
	global_load_dwordx4 v[136:139], v2, vcc offset:16
	global_load_dwordx4 v[140:143], v2, vcc offset:32
	global_load_dwordx4 v[144:147], v2, vcc offset:48
	s_mov_b64 exec, -1
	v_add_u32_e32 v198, 128, v199
	v_max_i32_e32 v198, 0, v198
	v_min_u32_e32 v198, 0x1fff, v198
	v_mul_lo_u32 v1, v198, s11
	v_add_u32_e32 v1, v1, v197
	v_lshlrev_b32_e32 v2, 6, v198
	global_load_dwordx4 v[20:23], v1, s[18:19] offset:2048
	global_load_dwordx4 v[24:27], v1, s[18:19] offset:2560
	s_mov_b64 exec, s[16:17]
	global_load_dwordx4 v[148:151], v2, vcc offset:0
	global_load_dwordx4 v[152:155], v2, vcc offset:16
	global_load_dwordx4 v[156:159], v2, vcc offset:32
	global_load_dwordx4 v[160:163], v2, vcc offset:48
	s_mov_b64 exec, -1
	v_add_u32_e32 v198, 192, v199
	v_max_i32_e32 v198, 0, v198
	v_min_u32_e32 v198, 0x1fff, v198
	v_mul_lo_u32 v1, v198, s11
	v_add_u32_e32 v1, v1, v197
	v_lshlrev_b32_e32 v2, 6, v198
	global_load_dwordx4 v[28:31], v1, s[18:19] offset:2048
	global_load_dwordx4 v[32:35], v1, s[18:19] offset:2560
	s_mov_b64 exec, s[16:17]
	global_load_dwordx4 v[84:87], v2, vcc offset:0
	global_load_dwordx4 v[88:91], v2, vcc offset:16
	global_load_dwordx4 v[92:95], v2, vcc offset:32
	global_load_dwordx4 v[96:99], v2, vcc offset:48
	s_mov_b64 exec, -1
	v_add_u32_e32 v198, 256, v199
	v_max_i32_e32 v198, 0, v198
	v_min_u32_e32 v198, 0x1fff, v198
	v_mul_lo_u32 v1, v198, s11
	v_add_u32_e32 v1, v1, v197
	v_lshlrev_b32_e32 v2, 6, v198
	global_load_dwordx4 v[36:39], v1, s[18:19] offset:2048
	global_load_dwordx4 v[40:43], v1, s[18:19] offset:2560
	s_mov_b64 exec, s[16:17]
	global_load_dwordx4 v[234:237], v2, vcc offset:0
	global_load_dwordx4 v[238:241], v2, vcc offset:16
	global_load_dwordx4 v[242:245], v2, vcc offset:32
	global_load_dwordx4 v[246:249], v2, vcc offset:48
	s_mov_b64 exec, -1
	v_add_u32_e32 v198, 320, v199
	v_max_i32_e32 v198, 0, v198
	v_min_u32_e32 v198, 0x1fff, v198
	v_mul_lo_u32 v1, v198, s11
	v_add_u32_e32 v1, v1, v197
	v_lshlrev_b32_e32 v2, 6, v198
	global_load_dwordx4 v[44:47], v1, s[18:19] offset:2048
	global_load_dwordx4 v[48:51], v1, s[18:19] offset:2560
	s_mov_b64 exec, s[16:17]
	global_load_dwordx4 v[100:103], v2, vcc offset:0
	global_load_dwordx4 v[104:107], v2, vcc offset:16
	global_load_dwordx4 v[108:111], v2, vcc offset:32
	global_load_dwordx4 v[164:167], v2, vcc offset:48
	s_mov_b64 exec, -1
	s_cmp_eq_u32 s24, 0
	s_cbranch_scc1 .Lat_skip0
	s_waitcnt vmcnt(30)
	v_lshlrev_b32_e32 v64, 16, v4
	v_and_b32_e32 v65, 0xffff0000, v4
	v_lshlrev_b32_e32 v66, 16, v5
	v_and_b32_e32 v67, 0xffff0000, v5
	v_lshlrev_b32_e32 v68, 16, v6
	v_and_b32_e32 v69, 0xffff0000, v6
	v_lshlrev_b32_e32 v70, 16, v7
	v_and_b32_e32 v71, 0xffff0000, v7
	v_mul_f32_e32 v60, v64, v64
	v_fmac_f32_e32 v60, v65, v65
	v_fmac_f32_e32 v60, v66, v66
	v_fmac_f32_e32 v60, v67, v67
	v_fmac_f32_e32 v60, v68, v68
	v_fmac_f32_e32 v60, v69, v69
	v_fmac_f32_e32 v60, v70, v70
	v_fmac_f32_e32 v60, v71, v71
	s_nop 1
	v_add_f32_dpp v60, v60, v60 quad_perm:[1,0,3,2] row_mask:0xf bank_mask:0xf
	s_nop 1
	v_add_f32_dpp v60, v60, v60 quad_perm:[2,3,0,1] row_mask:0xf bank_mask:0xf
	s_nop 1
	v_add_f32_dpp v60, v60, v60 row_half_mirror row_mask:0xf bank_mask:0xf
	s_nop 1
	v_fmamk_f32 v60, v60, 0x3c800000, v174
	v_rsq_f32_e32 v61, v60
	s_nop 0
	v_mul_f32_e32 v64, v64, v61
	v_mul_f32_e32 v65, v65, v61
	v_mul_f32_e32 v66, v66, v61
	v_mul_f32_e32 v67, v67, v61
	v_mul_f32_e32 v68, v68, v61
	v_mul_f32_e32 v69, v69, v61
	v_mul_f32_e32 v70, v70, v61
	v_mul_f32_e32 v71, v71, v61
	v_mul_f32_e32 v64, v64, v52
	v_mul_f32_e32 v65, v65, v53
	v_mul_f32_e32 v66, v66, v54
	v_mul_f32_e32 v67, v67, v55
	v_mul_f32_e32 v68, v68, v56
	v_mul_f32_e32 v69, v69, v57
	v_mul_f32_e32 v70, v70, v58
	v_mul_f32_e32 v71, v71, v59
	s_mov_b64 exec, s[16:17]
	s_nop 4
	v_mov_b32_dpp v72, v64 quad_perm:[1,0,3,2] row_mask:0xf bank_mask:0xf
	v_mov_b32_dpp v73, v65 quad_perm:[1,0,3,2] row_mask:0xf bank_mask:0xf
	v_mov_b32_dpp v74, v66 quad_perm:[1,0,3,2] row_mask:0xf bank_mask:0xf
	v_mov_b32_dpp v75, v67 quad_perm:[1,0,3,2] row_mask:0xf bank_mask:0xf
	v_mov_b32_dpp v76, v68 quad_perm:[1,0,3,2] row_mask:0xf bank_mask:0xf
	v_mov_b32_dpp v77, v69 quad_perm:[1,0,3,2] row_mask:0xf bank_mask:0xf
	v_mov_b32_dpp v78, v70 quad_perm:[1,0,3,2] row_mask:0xf bank_mask:0xf
	v_mov_b32_dpp v79, v71 quad_perm:[1,0,3,2] row_mask:0xf bank_mask:0xf
	s_nop 0
	v_mul_f32_e32 v72, v72, v117
	v_mul_f32_e32 v73, v73, v119
	v_mul_f32_e32 v74, v74, v121
	v_mul_f32_e32 v75, v75, v123
	v_mul_f32_e32 v76, v76, v125
	v_mul_f32_e32 v77, v77, v127
	v_mul_f32_e32 v78, v78, v129
	v_mul_f32_e32 v79, v79, v131
	v_cndmask_b32_e64 v72, v72, -v72, s[26:27]
	v_cndmask_b32_e64 v73, v73, -v73, s[26:27]
	v_cndmask_b32_e64 v74, v74, -v74, s[26:27]
	v_cndmask_b32_e64 v75, v75, -v75, s[26:27]
	v_cndmask_b32_e64 v76, v76, -v76, s[26:27]
	v_cndmask_b32_e64 v77, v77, -v77, s[26:27]
	v_cndmask_b32_e64 v78, v78, -v78, s[26:27]
	v_cndmask_b32_e64 v79, v79, -v79, s[26:27]
	v_fma_f32 v64, v64, v116, v72
	v_fma_f32 v65, v65, v118, v73
	v_fma_f32 v66, v66, v120, v74
	v_fma_f32 v67, v67, v122, v75
	v_fma_f32 v68, v68, v124, v76
	v_fma_f32 v69, v69, v126, v77
	v_fma_f32 v70, v70, v128, v78
	v_fma_f32 v71, v71, v130, v79
	s_mov_b64 exec, -1
	v_cvt_pk_bf16_f32 v80, v64, v65
	v_cvt_pk_bf16_f32 v81, v66, v67
	v_cvt_pk_bf16_f32 v82, v68, v69
	v_cvt_pk_bf16_f32 v83, v70, v71
	ds_write_b128 v3, v[80:83] offset:0
	ds_write_b128 v200, v[8:11] offset:0
.Lat_skip0:
	s_cmp_eq_u32 s24, 0
	s_cbranch_scc1 .Lat_skip1
	s_waitcnt vmcnt(24)
	v_lshlrev_b32_e32 v64, 16, v12
	v_and_b32_e32 v65, 0xffff0000, v12
	v_lshlrev_b32_e32 v66, 16, v13
	v_and_b32_e32 v67, 0xffff0000, v13
	v_lshlrev_b32_e32 v68, 16, v14
	v_and_b32_e32 v69, 0xffff0000, v14
	v_lshlrev_b32_e32 v70, 16, v15
	v_and_b32_e32 v71, 0xffff0000, v15
	v_mul_f32_e32 v60, v64, v64
	v_fmac_f32_e32 v60, v65, v65
	v_fmac_f32_e32 v60, v66, v66
	v_fmac_f32_e32 v60, v67, v67
	v_fmac_f32_e32 v60, v68, v68
	v_fmac_f32_e32 v60, v69, v69
	v_fmac_f32_e32 v60, v70, v70
	v_fmac_f32_e32 v60, v71, v71
	s_nop 1
	v_add_f32_dpp v60, v60, v60 quad_perm:[1,0,3,2] row_mask:0xf bank_mask:0xf
	s_nop 1
	v_add_f32_dpp v60, v60, v60 quad_perm:[2,3,0,1] row_mask:0xf bank_mask:0xf
	s_nop 1
	v_add_f32_dpp v60, v60, v60 row_half_mirror row_mask:0xf bank_mask:0xf
	s_nop 1
	v_fmamk_f32 v60, v60, 0x3c800000, v174
	v_rsq_f32_e32 v61, v60
	s_nop 0
	v_mul_f32_e32 v64, v64, v61
	v_mul_f32_e32 v65, v65, v61
	v_mul_f32_e32 v66, v66, v61
	v_mul_f32_e32 v67, v67, v61
	v_mul_f32_e32 v68, v68, v61
	v_mul_f32_e32 v69, v69, v61
	v_mul_f32_e32 v70, v70, v61
	v_mul_f32_e32 v71, v71, v61
	v_mul_f32_e32 v64, v64, v52
	v_mul_f32_e32 v65, v65, v53
	v_mul_f32_e32 v66, v66, v54
	v_mul_f32_e32 v67, v67, v55
	v_mul_f32_e32 v68, v68, v56
	v_mul_f32_e32 v69, v69, v57
	v_mul_f32_e32 v70, v70, v58
	v_mul_f32_e32 v71, v71, v59
	s_mov_b64 exec, s[16:17]
	s_nop 4
	v_mov_b32_dpp v72, v64 quad_perm:[1,0,3,2] row_mask:0xf bank_mask:0xf
	v_mov_b32_dpp v73, v65 quad_perm:[1,0,3,2] row_mask:0xf bank_mask:0xf
	v_mov_b32_dpp v74, v66 quad_perm:[1,0,3,2] row_mask:0xf bank_mask:0xf
	v_mov_b32_dpp v75, v67 quad_perm:[1,0,3,2] row_mask:0xf bank_mask:0xf
	v_mov_b32_dpp v76, v68 quad_perm:[1,0,3,2] row_mask:0xf bank_mask:0xf
	v_mov_b32_dpp v77, v69 quad_perm:[1,0,3,2] row_mask:0xf bank_mask:0xf
	v_mov_b32_dpp v78, v70 quad_perm:[1,0,3,2] row_mask:0xf bank_mask:0xf
	v_mov_b32_dpp v79, v71 quad_perm:[1,0,3,2] row_mask:0xf bank_mask:0xf
	s_nop 0
	v_mul_f32_e32 v72, v72, v133
	v_mul_f32_e32 v73, v73, v135
	v_mul_f32_e32 v74, v74, v137
	v_mul_f32_e32 v75, v75, v139
	v_mul_f32_e32 v76, v76, v141
	v_mul_f32_e32 v77, v77, v143
	v_mul_f32_e32 v78, v78, v145
	v_mul_f32_e32 v79, v79, v147
	v_cndmask_b32_e64 v72, v72, -v72, s[26:27]
	v_cndmask_b32_e64 v73, v73, -v73, s[26:27]
	v_cndmask_b32_e64 v74, v74, -v74, s[26:27]
	v_cndmask_b32_e64 v75, v75, -v75, s[26:27]
	v_cndmask_b32_e64 v76, v76, -v76, s[26:27]
	v_cndmask_b32_e64 v77, v77, -v77, s[26:27]
	v_cndmask_b32_e64 v78, v78, -v78, s[26:27]
	v_cndmask_b32_e64 v79, v79, -v79, s[26:27]
	v_fma_f32 v64, v64, v132, v72
	v_fma_f32 v65, v65, v134, v73
	v_fma_f32 v66, v66, v136, v74
	v_fma_f32 v67, v67, v138, v75
	v_fma_f32 v68, v68, v140, v76
	v_fma_f32 v69, v69, v142, v77
	v_fma_f32 v70, v70, v144, v78
	v_fma_f32 v71, v71, v146, v79
	s_mov_b64 exec, -1
	v_cvt_pk_bf16_f32 v80, v64, v65
	v_cvt_pk_bf16_f32 v81, v66, v67
	v_cvt_pk_bf16_f32 v82, v68, v69
	v_cvt_pk_bf16_f32 v83, v70, v71
	ds_write_b128 v3, v[80:83] offset:9216
	ds_write_b128 v200, v[16:19] offset:9216
.Lat_skip1:
	s_waitcnt vmcnt(18)
	v_lshlrev_b32_e32 v64, 16, v20
	v_and_b32_e32 v65, 0xffff0000, v20
	v_lshlrev_b32_e32 v66, 16, v21
	v_and_b32_e32 v67, 0xffff0000, v21
	v_lshlrev_b32_e32 v68, 16, v22
	v_and_b32_e32 v69, 0xffff0000, v22
	v_lshlrev_b32_e32 v70, 16, v23
	v_and_b32_e32 v71, 0xffff0000, v23
	v_mul_f32_e32 v60, v64, v64
	v_fmac_f32_e32 v60, v65, v65
	v_fmac_f32_e32 v60, v66, v66
	v_fmac_f32_e32 v60, v67, v67
	v_fmac_f32_e32 v60, v68, v68
	v_fmac_f32_e32 v60, v69, v69
	v_fmac_f32_e32 v60, v70, v70
	v_fmac_f32_e32 v60, v71, v71
	s_nop 1
	v_add_f32_dpp v60, v60, v60 quad_perm:[1,0,3,2] row_mask:0xf bank_mask:0xf
	s_nop 1
	v_add_f32_dpp v60, v60, v60 quad_perm:[2,3,0,1] row_mask:0xf bank_mask:0xf
	s_nop 1
	v_add_f32_dpp v60, v60, v60 row_half_mirror row_mask:0xf bank_mask:0xf
	s_nop 1
	v_fmamk_f32 v60, v60, 0x3c800000, v174
	v_rsq_f32_e32 v61, v60
	s_nop 0
	v_mul_f32_e32 v64, v64, v61
	v_mul_f32_e32 v65, v65, v61
	v_mul_f32_e32 v66, v66, v61
	v_mul_f32_e32 v67, v67, v61
	v_mul_f32_e32 v68, v68, v61
	v_mul_f32_e32 v69, v69, v61
	v_mul_f32_e32 v70, v70, v61
	v_mul_f32_e32 v71, v71, v61
	v_mul_f32_e32 v64, v64, v52
	v_mul_f32_e32 v65, v65, v53
	v_mul_f32_e32 v66, v66, v54
	v_mul_f32_e32 v67, v67, v55
	v_mul_f32_e32 v68, v68, v56
	v_mul_f32_e32 v69, v69, v57
	v_mul_f32_e32 v70, v70, v58
	v_mul_f32_e32 v71, v71, v59
	s_mov_b64 exec, s[16:17]
	s_nop 4
	v_mov_b32_dpp v72, v64 quad_perm:[1,0,3,2] row_mask:0xf bank_mask:0xf
	v_mov_b32_dpp v73, v65 quad_perm:[1,0,3,2] row_mask:0xf bank_mask:0xf
	v_mov_b32_dpp v74, v66 quad_perm:[1,0,3,2] row_mask:0xf bank_mask:0xf
	v_mov_b32_dpp v75, v67 quad_perm:[1,0,3,2] row_mask:0xf bank_mask:0xf
	v_mov_b32_dpp v76, v68 quad_perm:[1,0,3,2] row_mask:0xf bank_mask:0xf
	v_mov_b32_dpp v77, v69 quad_perm:[1,0,3,2] row_mask:0xf bank_mask:0xf
	v_mov_b32_dpp v78, v70 quad_perm:[1,0,3,2] row_mask:0xf bank_mask:0xf
	v_mov_b32_dpp v79, v71 quad_perm:[1,0,3,2] row_mask:0xf bank_mask:0xf
	s_nop 0
	v_mul_f32_e32 v72, v72, v149
	v_mul_f32_e32 v73, v73, v151
	v_mul_f32_e32 v74, v74, v153
	v_mul_f32_e32 v75, v75, v155
	v_mul_f32_e32 v76, v76, v157
	v_mul_f32_e32 v77, v77, v159
	v_mul_f32_e32 v78, v78, v161
	v_mul_f32_e32 v79, v79, v163
	v_cndmask_b32_e64 v72, v72, -v72, s[26:27]
	v_cndmask_b32_e64 v73, v73, -v73, s[26:27]
	v_cndmask_b32_e64 v74, v74, -v74, s[26:27]
	v_cndmask_b32_e64 v75, v75, -v75, s[26:27]
	v_cndmask_b32_e64 v76, v76, -v76, s[26:27]
	v_cndmask_b32_e64 v77, v77, -v77, s[26:27]
	v_cndmask_b32_e64 v78, v78, -v78, s[26:27]
	v_cndmask_b32_e64 v79, v79, -v79, s[26:27]
	v_fma_f32 v64, v64, v148, v72
	v_fma_f32 v65, v65, v150, v73
	v_fma_f32 v66, v66, v152, v74
	v_fma_f32 v67, v67, v154, v75
	v_fma_f32 v68, v68, v156, v76
	v_fma_f32 v69, v69, v158, v77
	v_fma_f32 v70, v70, v160, v78
	v_fma_f32 v71, v71, v162, v79
	s_mov_b64 exec, -1
	v_cvt_pk_bf16_f32 v80, v64, v65
	v_cvt_pk_bf16_f32 v81, v66, v67
	v_cvt_pk_bf16_f32 v82, v68, v69
	v_cvt_pk_bf16_f32 v83, v70, v71
	ds_write_b128 v3, v[80:83] offset:18432
	ds_write_b128 v200, v[24:27] offset:18432
.Lat_skip2:
	s_waitcnt vmcnt(12)
	v_lshlrev_b32_e32 v64, 16, v28
	v_and_b32_e32 v65, 0xffff0000, v28
	v_lshlrev_b32_e32 v66, 16, v29
	v_and_b32_e32 v67, 0xffff0000, v29
	v_lshlrev_b32_e32 v68, 16, v30
	v_and_b32_e32 v69, 0xffff0000, v30
	v_lshlrev_b32_e32 v70, 16, v31
	v_and_b32_e32 v71, 0xffff0000, v31
	v_mul_f32_e32 v60, v64, v64
	v_fmac_f32_e32 v60, v65, v65
	v_fmac_f32_e32 v60, v66, v66
	v_fmac_f32_e32 v60, v67, v67
	v_fmac_f32_e32 v60, v68, v68
	v_fmac_f32_e32 v60, v69, v69
	v_fmac_f32_e32 v60, v70, v70
	v_fmac_f32_e32 v60, v71, v71
	s_nop 1
	v_add_f32_dpp v60, v60, v60 quad_perm:[1,0,3,2] row_mask:0xf bank_mask:0xf
	s_nop 1
	v_add_f32_dpp v60, v60, v60 quad_perm:[2,3,0,1] row_mask:0xf bank_mask:0xf
	s_nop 1
	v_add_f32_dpp v60, v60, v60 row_half_mirror row_mask:0xf bank_mask:0xf
	s_nop 1
	v_fmamk_f32 v60, v60, 0x3c800000, v174
	v_rsq_f32_e32 v61, v60
	s_nop 0
	v_mul_f32_e32 v64, v64, v61
	v_mul_f32_e32 v65, v65, v61
	v_mul_f32_e32 v66, v66, v61
	v_mul_f32_e32 v67, v67, v61
	v_mul_f32_e32 v68, v68, v61
	v_mul_f32_e32 v69, v69, v61
	v_mul_f32_e32 v70, v70, v61
	v_mul_f32_e32 v71, v71, v61
	v_mul_f32_e32 v64, v64, v52
	v_mul_f32_e32 v65, v65, v53
	v_mul_f32_e32 v66, v66, v54
	v_mul_f32_e32 v67, v67, v55
	v_mul_f32_e32 v68, v68, v56
	v_mul_f32_e32 v69, v69, v57
	v_mul_f32_e32 v70, v70, v58
	v_mul_f32_e32 v71, v71, v59
	s_mov_b64 exec, s[16:17]
	s_nop 4
	v_mov_b32_dpp v72, v64 quad_perm:[1,0,3,2] row_mask:0xf bank_mask:0xf
	v_mov_b32_dpp v73, v65 quad_perm:[1,0,3,2] row_mask:0xf bank_mask:0xf
	v_mov_b32_dpp v74, v66 quad_perm:[1,0,3,2] row_mask:0xf bank_mask:0xf
	v_mov_b32_dpp v75, v67 quad_perm:[1,0,3,2] row_mask:0xf bank_mask:0xf
	v_mov_b32_dpp v76, v68 quad_perm:[1,0,3,2] row_mask:0xf bank_mask:0xf
	v_mov_b32_dpp v77, v69 quad_perm:[1,0,3,2] row_mask:0xf bank_mask:0xf
	v_mov_b32_dpp v78, v70 quad_perm:[1,0,3,2] row_mask:0xf bank_mask:0xf
	v_mov_b32_dpp v79, v71 quad_perm:[1,0,3,2] row_mask:0xf bank_mask:0xf
	s_nop 0
	v_mul_f32_e32 v72, v72, v85
	v_mul_f32_e32 v73, v73, v87
	v_mul_f32_e32 v74, v74, v89
	v_mul_f32_e32 v75, v75, v91
	v_mul_f32_e32 v76, v76, v93
	v_mul_f32_e32 v77, v77, v95
	v_mul_f32_e32 v78, v78, v97
	v_mul_f32_e32 v79, v79, v99
	v_cndmask_b32_e64 v72, v72, -v72, s[26:27]
	v_cndmask_b32_e64 v73, v73, -v73, s[26:27]
	v_cndmask_b32_e64 v74, v74, -v74, s[26:27]
	v_cndmask_b32_e64 v75, v75, -v75, s[26:27]
	v_cndmask_b32_e64 v76, v76, -v76, s[26:27]
	v_cndmask_b32_e64 v77, v77, -v77, s[26:27]
	v_cndmask_b32_e64 v78, v78, -v78, s[26:27]
	v_cndmask_b32_e64 v79, v79, -v79, s[26:27]
	v_fma_f32 v64, v64, v84, v72
	v_fma_f32 v65, v65, v86, v73
	v_fma_f32 v66, v66, v88, v74
	v_fma_f32 v67, v67, v90, v75
	v_fma_f32 v68, v68, v92, v76
	v_fma_f32 v69, v69, v94, v77
	v_fma_f32 v70, v70, v96, v78
	v_fma_f32 v71, v71, v98, v79
	s_mov_b64 exec, -1
	v_cvt_pk_bf16_f32 v80, v64, v65
	v_cvt_pk_bf16_f32 v81, v66, v67
	v_cvt_pk_bf16_f32 v82, v68, v69
	v_cvt_pk_bf16_f32 v83, v70, v71
	ds_write_b128 v3, v[80:83] offset:27648
	ds_write_b128 v200, v[32:35] offset:27648
.Lat_skip3:
	s_cmp_eq_u32 s24, 63
	s_cbranch_scc1 .Lat_skip4
	s_waitcnt vmcnt(6)
	v_lshlrev_b32_e32 v64, 16, v36
	v_and_b32_e32 v65, 0xffff0000, v36
	v_lshlrev_b32_e32 v66, 16, v37
	v_and_b32_e32 v67, 0xffff0000, v37
	v_lshlrev_b32_e32 v68, 16, v38
	v_and_b32_e32 v69, 0xffff0000, v38
	v_lshlrev_b32_e32 v70, 16, v39
	v_and_b32_e32 v71, 0xffff0000, v39
	v_mul_f32_e32 v60, v64, v64
	v_fmac_f32_e32 v60, v65, v65
	v_fmac_f32_e32 v60, v66, v66
	v_fmac_f32_e32 v60, v67, v67
	v_fmac_f32_e32 v60, v68, v68
	v_fmac_f32_e32 v60, v69, v69
	v_fmac_f32_e32 v60, v70, v70
	v_fmac_f32_e32 v60, v71, v71
	s_nop 1
	v_add_f32_dpp v60, v60, v60 quad_perm:[1,0,3,2] row_mask:0xf bank_mask:0xf
	s_nop 1
	v_add_f32_dpp v60, v60, v60 quad_perm:[2,3,0,1] row_mask:0xf bank_mask:0xf
	s_nop 1
	v_add_f32_dpp v60, v60, v60 row_half_mirror row_mask:0xf bank_mask:0xf
	s_nop 1
	v_fmamk_f32 v60, v60, 0x3c800000, v174
	v_rsq_f32_e32 v61, v60
	s_nop 0
	v_mul_f32_e32 v64, v64, v61
	v_mul_f32_e32 v65, v65, v61
	v_mul_f32_e32 v66, v66, v61
	v_mul_f32_e32 v67, v67, v61
	v_mul_f32_e32 v68, v68, v61
	v_mul_f32_e32 v69, v69, v61
	v_mul_f32_e32 v70, v70, v61
	v_mul_f32_e32 v71, v71, v61
	v_mul_f32_e32 v64, v64, v52
	v_mul_f32_e32 v65, v65, v53
	v_mul_f32_e32 v66, v66, v54
	v_mul_f32_e32 v67, v67, v55
	v_mul_f32_e32 v68, v68, v56
	v_mul_f32_e32 v69, v69, v57
	v_mul_f32_e32 v70, v70, v58
	v_mul_f32_e32 v71, v71, v59
	s_mov_b64 exec, s[16:17]
	s_nop 4
	v_mov_b32_dpp v72, v64 quad_perm:[1,0,3,2] row_mask:0xf bank_mask:0xf
	v_mov_b32_dpp v73, v65 quad_perm:[1,0,3,2] row_mask:0xf bank_mask:0xf
	v_mov_b32_dpp v74, v66 quad_perm:[1,0,3,2] row_mask:0xf bank_mask:0xf
	v_mov_b32_dpp v75, v67 quad_perm:[1,0,3,2] row_mask:0xf bank_mask:0xf
	v_mov_b32_dpp v76, v68 quad_perm:[1,0,3,2] row_mask:0xf bank_mask:0xf
	v_mov_b32_dpp v77, v69 quad_perm:[1,0,3,2] row_mask:0xf bank_mask:0xf
	v_mov_b32_dpp v78, v70 quad_perm:[1,0,3,2] row_mask:0xf bank_mask:0xf
	v_mov_b32_dpp v79, v71 quad_perm:[1,0,3,2] row_mask:0xf bank_mask:0xf
	s_nop 0
	v_mul_f32_e32 v72, v72, v235
	v_mul_f32_e32 v73, v73, v237
	v_mul_f32_e32 v74, v74, v239
	v_mul_f32_e32 v75, v75, v241
	v_mul_f32_e32 v76, v76, v243
	v_mul_f32_e32 v77, v77, v245
	v_mul_f32_e32 v78, v78, v247
	v_mul_f32_e32 v79, v79, v249
	v_cndmask_b32_e64 v72, v72, -v72, s[26:27]
	v_cndmask_b32_e64 v73, v73, -v73, s[26:27]
	v_cndmask_b32_e64 v74, v74, -v74, s[26:27]
	v_cndmask_b32_e64 v75, v75, -v75, s[26:27]
	v_cndmask_b32_e64 v76, v76, -v76, s[26:27]
	v_cndmask_b32_e64 v77, v77, -v77, s[26:27]
	v_cndmask_b32_e64 v78, v78, -v78, s[26:27]
	v_cndmask_b32_e64 v79, v79, -v79, s[26:27]
	v_fma_f32 v64, v64, v234, v72
	v_fma_f32 v65, v65, v236, v73
	v_fma_f32 v66, v66, v238, v74
	v_fma_f32 v67, v67, v240, v75
	v_fma_f32 v68, v68, v242, v76
	v_fma_f32 v69, v69, v244, v77
	v_fma_f32 v70, v70, v246, v78
	v_fma_f32 v71, v71, v248, v79
	s_mov_b64 exec, -1
	v_cvt_pk_bf16_f32 v80, v64, v65
	v_cvt_pk_bf16_f32 v81, v66, v67
	v_cvt_pk_bf16_f32 v82, v68, v69
	v_cvt_pk_bf16_f32 v83, v70, v71
	ds_write_b128 v3, v[80:83] offset:36864
	ds_write_b128 v200, v[40:43] offset:36864
.Lat_skip4:
	s_cmp_eq_u32 s24, 63
	s_cbranch_scc1 .Lat_skip5
	s_waitcnt vmcnt(0)
	v_lshlrev_b32_e32 v64, 16, v44
	v_and_b32_e32 v65, 0xffff0000, v44
	v_lshlrev_b32_e32 v66, 16, v45
	v_and_b32_e32 v67, 0xffff0000, v45
	v_lshlrev_b32_e32 v68, 16, v46
	v_and_b32_e32 v69, 0xffff0000, v46
	v_lshlrev_b32_e32 v70, 16, v47
	v_and_b32_e32 v71, 0xffff0000, v47
	v_mul_f32_e32 v60, v64, v64
	v_fmac_f32_e32 v60, v65, v65
	v_fmac_f32_e32 v60, v66, v66
	v_fmac_f32_e32 v60, v67, v67
	v_fmac_f32_e32 v60, v68, v68
	v_fmac_f32_e32 v60, v69, v69
	v_fmac_f32_e32 v60, v70, v70
	v_fmac_f32_e32 v60, v71, v71
	s_nop 1
	v_add_f32_dpp v60, v60, v60 quad_perm:[1,0,3,2] row_mask:0xf bank_mask:0xf
	s_nop 1
	v_add_f32_dpp v60, v60, v60 quad_perm:[2,3,0,1] row_mask:0xf bank_mask:0xf
	s_nop 1
	v_add_f32_dpp v60, v60, v60 row_half_mirror row_mask:0xf bank_mask:0xf
	s_nop 1
	v_fmamk_f32 v60, v60, 0x3c800000, v174
	v_rsq_f32_e32 v61, v60
	s_nop 0
	v_mul_f32_e32 v64, v64, v61
	v_mul_f32_e32 v65, v65, v61
	v_mul_f32_e32 v66, v66, v61
	v_mul_f32_e32 v67, v67, v61
	v_mul_f32_e32 v68, v68, v61
	v_mul_f32_e32 v69, v69, v61
	v_mul_f32_e32 v70, v70, v61
	v_mul_f32_e32 v71, v71, v61
	v_mul_f32_e32 v64, v64, v52
	v_mul_f32_e32 v65, v65, v53
	v_mul_f32_e32 v66, v66, v54
	v_mul_f32_e32 v67, v67, v55
	v_mul_f32_e32 v68, v68, v56
	v_mul_f32_e32 v69, v69, v57
	v_mul_f32_e32 v70, v70, v58
	v_mul_f32_e32 v71, v71, v59
	s_mov_b64 exec, s[16:17]
	s_nop 4
	v_mov_b32_dpp v72, v64 quad_perm:[1,0,3,2] row_mask:0xf bank_mask:0xf
	v_mov_b32_dpp v73, v65 quad_perm:[1,0,3,2] row_mask:0xf bank_mask:0xf
	v_mov_b32_dpp v74, v66 quad_perm:[1,0,3,2] row_mask:0xf bank_mask:0xf
	v_mov_b32_dpp v75, v67 quad_perm:[1,0,3,2] row_mask:0xf bank_mask:0xf
	v_mov_b32_dpp v76, v68 quad_perm:[1,0,3,2] row_mask:0xf bank_mask:0xf
	v_mov_b32_dpp v77, v69 quad_perm:[1,0,3,2] row_mask:0xf bank_mask:0xf
	v_mov_b32_dpp v78, v70 quad_perm:[1,0,3,2] row_mask:0xf bank_mask:0xf
	v_mov_b32_dpp v79, v71 quad_perm:[1,0,3,2] row_mask:0xf bank_mask:0xf
	s_nop 0
	v_mul_f32_e32 v72, v72, v101
	v_mul_f32_e32 v73, v73, v103
	v_mul_f32_e32 v74, v74, v105
	v_mul_f32_e32 v75, v75, v107
	v_mul_f32_e32 v76, v76, v109
	v_mul_f32_e32 v77, v77, v111
	v_mul_f32_e32 v78, v78, v165
	v_mul_f32_e32 v79, v79, v167
	v_cndmask_b32_e64 v72, v72, -v72, s[26:27]
	v_cndmask_b32_e64 v73, v73, -v73, s[26:27]
	v_cndmask_b32_e64 v74, v74, -v74, s[26:27]
	v_cndmask_b32_e64 v75, v75, -v75, s[26:27]
	v_cndmask_b32_e64 v76, v76, -v76, s[26:27]
	v_cndmask_b32_e64 v77, v77, -v77, s[26:27]
	v_cndmask_b32_e64 v78, v78, -v78, s[26:27]
	v_cndmask_b32_e64 v79, v79, -v79, s[26:27]
	v_fma_f32 v64, v64, v100, v72
	v_fma_f32 v65, v65, v102, v73
	v_fma_f32 v66, v66, v104, v74
	v_fma_f32 v67, v67, v106, v75
	v_fma_f32 v68, v68, v108, v76
	v_fma_f32 v69, v69, v110, v77
	v_fma_f32 v70, v70, v164, v78
	v_fma_f32 v71, v71, v166, v79
	s_mov_b64 exec, -1
	v_cvt_pk_bf16_f32 v80, v64, v65
	v_cvt_pk_bf16_f32 v81, v66, v67
	v_cvt_pk_bf16_f32 v82, v68, v69
	v_cvt_pk_bf16_f32 v83, v70, v71
	ds_write_b128 v3, v[80:83] offset:46080
	ds_write_b128 v200, v[48:51] offset:46080
.Lat_skip5:
	s_waitcnt vmcnt(0)
	s_waitcnt lgkmcnt(0)
.LBB0_357:
	s_lshl_b32 s3, s3, 2
	s_add_i32 s18, s3, s21
	s_lshl_b32 s16, s18, 6
	v_or_b32_e32 v1, s10, v186
	s_ashr_i32 s17, s16, 31
	s_waitcnt vmcnt(0)
	v_lshl_add_u64 v[2:3], s[16:17], 1, v[170:171]
	v_or_b32_e32 v180, s14, v1
	s_movk_i32 s3, 0xc00
	v_or_b32_e32 v6, 32, v1
	v_mad_u64_u32 v[4:5], s[10:11], v180, s3, v[2:3]
	v_or_b32_e32 v7, s14, v6
	v_mad_i32_i24 v5, s15, v230, v5
	v_mad_u64_u32 v[2:3], s[10:11], v7, s3, v[2:3]
	global_load_dwordx4 v[58:61], v[4:5], off offset:96
	v_mad_i32_i24 v3, s15, v230, v3
	global_load_dwordx4 v[62:65], v[2:3], off offset:96
	global_load_dwordx4 v[84:87], v[4:5], off offset:64
	global_load_dwordx4 v[88:91], v[2:3], off offset:64
	global_load_dwordx4 v[34:37], v[4:5], off offset:32
	global_load_dwordx4 v[30:33], v[2:3], off offset:32
	global_load_dwordx4 v[66:69], v[4:5], off
	v_readlane_b32 s10, v253, 10
	v_lshlrev_b32_e32 v1, 6, v1
	v_readlane_b32 s11, v253, 11
	global_load_dwordx4 v[108:111], v[2:3], off
	v_lshlrev_b32_e32 v96, 6, v6
	s_mov_b32 s3, 0x800000
	s_ashr_i32 s19, s18, 31
	v_mov_b32_e32 v181, s15
	global_load_dwordx4 v[46:49], v1, s[10:11] offset:48
	global_load_dwordx4 v[6:9], v96, s[10:11] offset:32
	global_load_dwordx4 v[2:5], v96, s[10:11] offset:48
	global_load_dwordx4 v[10:13], v[178:179], off offset:208
	global_load_dwordx4 v[14:17], v[178:179], off offset:192
	global_load_dwordx4 v[18:21], v[178:179], off offset:144
	global_load_dwordx4 v[22:25], v[178:179], off offset:128
	global_load_dwordx4 v[54:57], v1, s[10:11] offset:32
	global_load_dwordx4 v[26:29], v[178:179], off offset:80
	global_load_dwordx4 v[38:41], v[178:179], off offset:64
	global_load_dwordx4 v[42:45], v1, s[10:11]
	global_load_dwordx4 v[50:53], v1, s[10:11] offset:16
	s_mov_b32 s25, 0x800000
	v_mov_b32_e32 v197, v185
	s_waitcnt vmcnt(18)
	v_lshlrev_b32_e32 v70, 16, v65
	v_and_b32_e32 v71, 0xffff0000, v65
	v_lshlrev_b32_e32 v72, 16, v64
	v_lshlrev_b32_e32 v102, 16, v61
	v_and_b32_e32 v103, 0xffff0000, v61
	v_lshlrev_b32_e32 v104, 16, v60
	v_and_b32_e32 v105, 0xffff0000, v60
	v_and_b32_e32 v73, 0xffff0000, v64
	v_lshlrev_b32_e32 v106, 16, v59
	v_and_b32_e32 v107, 0xffff0000, v59
	v_lshlrev_b32_e32 v74, 16, v63
	v_and_b32_e32 v75, 0xffff0000, v63
	v_lshlrev_b32_e32 v116, 16, v58
	v_and_b32_e32 v117, 0xffff0000, v58
	v_lshlrev_b32_e32 v76, 16, v62
	v_and_b32_e32 v77, 0xffff0000, v62
	s_waitcnt vmcnt(17)
	v_lshlrev_b32_e32 v118, 16, v87
	v_and_b32_e32 v119, 0xffff0000, v87
	s_waitcnt vmcnt(16)
	v_lshlrev_b32_e32 v78, 16, v91
	v_and_b32_e32 v79, 0xffff0000, v91
	v_lshlrev_b32_e32 v120, 16, v86
	v_and_b32_e32 v121, 0xffff0000, v86
	v_lshlrev_b32_e32 v80, 16, v90
	v_and_b32_e32 v81, 0xffff0000, v90
	v_lshlrev_b32_e32 v122, 16, v85
	v_and_b32_e32 v123, 0xffff0000, v85
	v_lshlrev_b32_e32 v82, 16, v89
	v_and_b32_e32 v83, 0xffff0000, v89
	v_lshlrev_b32_e32 v124, 16, v84
	v_and_b32_e32 v125, 0xffff0000, v84
	v_lshlrev_b32_e32 v84, 16, v88
	v_and_b32_e32 v85, 0xffff0000, v88
	s_waitcnt vmcnt(15)
	v_lshlrev_b32_e32 v126, 16, v37
	v_and_b32_e32 v127, 0xffff0000, v37
	s_waitcnt vmcnt(14)
	v_lshlrev_b32_e32 v86, 16, v33
	v_and_b32_e32 v87, 0xffff0000, v33
	v_lshlrev_b32_e32 v128, 16, v36
	v_and_b32_e32 v129, 0xffff0000, v36
	v_lshlrev_b32_e32 v88, 16, v32
	v_and_b32_e32 v89, 0xffff0000, v32
	v_lshlrev_b32_e32 v152, 16, v35
	v_and_b32_e32 v153, 0xffff0000, v35
	v_lshlrev_b32_e32 v90, 16, v31
	v_and_b32_e32 v91, 0xffff0000, v31
	v_lshlrev_b32_e32 v154, 16, v34
	v_and_b32_e32 v155, 0xffff0000, v34
	v_lshlrev_b32_e32 v92, 16, v30
	v_and_b32_e32 v93, 0xffff0000, v30
	global_load_dwordx4 v[58:61], v[178:179], off offset:16
	global_load_dwordx4 v[62:65], v[178:179], off
	global_load_dwordx4 v[34:37], v96, s[10:11]
	global_load_dwordx4 v[30:33], v96, s[10:11] offset:16
	s_waitcnt vmcnt(16)
	v_lshlrev_b32_e32 v94, 16, v111
	v_and_b32_e32 v95, 0xffff0000, v111
	s_waitcnt vmcnt(8)
	v_mov_b32_e32 v100, v54
	v_mov_b32_e32 v101, v56
	v_mov_b32_e32 v56, v55
	v_lshlrev_b32_e32 v54, 16, v110
	v_and_b32_e32 v55, 0xffff0000, v110
	v_lshlrev_b32_e32 v110, 16, v67
	v_and_b32_e32 v111, 0xffff0000, v67
	v_and_b32_e32 v161, 0xffff0000, v66
	v_and_b32_e32 v67, 0xffff0000, v108
	v_lshlrev_b32_e32 v160, 16, v66
	v_lshlrev_b32_e32 v66, 16, v108
	v_mov_b32_e32 v162, v67
	v_mov_b32_e32 v163, v161
	v_lshlrev_b32_e32 v156, 16, v69
	v_and_b32_e32 v157, 0xffff0000, v69
	v_lshlrev_b32_e32 v158, 16, v68
	v_and_b32_e32 v159, 0xffff0000, v68
	v_lshlrev_b32_e32 v68, 16, v109
	v_and_b32_e32 v69, 0xffff0000, v109
	v_mov_b32_e32 v108, v66
	v_mov_b32_e32 v109, v160
	v_pk_mul_f32 v[162:163], v[162:163], v[162:163]
	v_mov_b32_e32 v98, v46
	v_mov_b32_e32 v99, v48
	v_mov_b32_e32 v48, v47
	v_mov_b32_e32 v46, v2
	v_mov_b32_e32 v47, v4
	v_mov_b32_e32 v4, v3
	v_mov_b32_e32 v2, v6
	v_mov_b32_e32 v3, v8
	v_mov_b32_e32 v8, v7
	v_mov_b32_e32 v6, v68
	v_mov_b32_e32 v7, v110
	v_pk_fma_f32 v[108:109], v[108:109], v[108:109], v[162:163]
	v_mov_b32_e32 v210, v69
	v_mov_b32_e32 v211, v111
	v_pk_fma_f32 v[6:7], v[6:7], v[6:7], v[108:109]
	v_mov_b32_e32 v206, v54
	v_mov_b32_e32 v207, v158
	v_pk_fma_f32 v[6:7], v[210:211], v[210:211], v[6:7]
	v_mov_b32_e32 v208, v55
	v_mov_b32_e32 v209, v159
	v_pk_fma_f32 v[6:7], v[206:207], v[206:207], v[6:7]
	v_mov_b32_e32 v202, v94
	v_mov_b32_e32 v203, v156
	v_pk_fma_f32 v[6:7], v[208:209], v[208:209], v[6:7]
	v_mov_b32_e32 v204, v95
	v_mov_b32_e32 v205, v157
	v_pk_fma_f32 v[6:7], v[202:203], v[202:203], v[6:7]
	v_mov_b32_e32 v198, v92
	v_mov_b32_e32 v199, v154
	v_pk_fma_f32 v[6:7], v[204:205], v[204:205], v[6:7]
	v_mov_b32_e32 v200, v93
	v_mov_b32_e32 v201, v155
	v_pk_fma_f32 v[6:7], v[198:199], v[198:199], v[6:7]
	v_mov_b32_e32 v164, v90
	v_mov_b32_e32 v165, v152
	v_pk_fma_f32 v[6:7], v[200:201], v[200:201], v[6:7]
	v_mov_b32_e32 v166, v91
	v_mov_b32_e32 v167, v153
	v_pk_fma_f32 v[6:7], v[164:165], v[164:165], v[6:7]
	v_mov_b32_e32 v162, v88
	v_mov_b32_e32 v163, v128
	v_pk_fma_f32 v[6:7], v[166:167], v[166:167], v[6:7]
	v_mov_b32_e32 v150, v89
	v_mov_b32_e32 v151, v129
	v_pk_fma_f32 v[6:7], v[162:163], v[162:163], v[6:7]
	v_mov_b32_e32 v202, v86
	v_mov_b32_e32 v203, v126
	v_pk_fma_f32 v[6:7], v[150:151], v[150:151], v[6:7]
	v_mov_b32_e32 v204, v87
	v_mov_b32_e32 v205, v127
	v_pk_fma_f32 v[6:7], v[202:203], v[202:203], v[6:7]
	v_mov_b32_e32 v198, v84
	v_mov_b32_e32 v199, v124
	v_pk_fma_f32 v[6:7], v[204:205], v[204:205], v[6:7]
	v_mov_b32_e32 v200, v85
	v_mov_b32_e32 v201, v125
	v_pk_fma_f32 v[6:7], v[198:199], v[198:199], v[6:7]
	v_mov_b32_e32 v164, v82
	v_mov_b32_e32 v165, v122
	v_pk_fma_f32 v[6:7], v[200:201], v[200:201], v[6:7]
	v_mov_b32_e32 v166, v83
	v_mov_b32_e32 v167, v123
	v_pk_fma_f32 v[6:7], v[164:165], v[164:165], v[6:7]
	v_mov_b32_e32 v108, v80
	v_mov_b32_e32 v109, v120
	v_pk_fma_f32 v[6:7], v[166:167], v[166:167], v[6:7]
	v_pk_mul_f32 v[146:147], v[118:119], v[118:119]
	v_pk_mul_f32 v[148:149], v[78:79], v[78:79]
	v_mov_b32_e32 v162, v81
	v_mov_b32_e32 v163, v121
	v_pk_fma_f32 v[6:7], v[108:109], v[108:109], v[6:7]
	v_mov_b32_e32 v108, v148
	v_pk_fma_f32 v[6:7], v[162:163], v[162:163], v[6:7]
	v_mov_b32_e32 v109, v146
	v_pk_mul_f32 v[142:143], v[116:117], v[116:117]
	v_pk_mul_f32 v[144:145], v[76:77], v[76:77]
	v_pk_add_f32 v[6:7], v[108:109], v[6:7]
	v_mov_b32_e32 v146, v149
	v_pk_add_f32 v[6:7], v[146:147], v[6:7]
	v_mov_b32_e32 v108, v144
	v_mov_b32_e32 v109, v142
	v_pk_mul_f32 v[138:139], v[106:107], v[106:107]
	v_pk_mul_f32 v[140:141], v[74:75], v[74:75]
	v_pk_add_f32 v[6:7], v[108:109], v[6:7]
	v_mov_b32_e32 v142, v145
	v_pk_add_f32 v[6:7], v[142:143], v[6:7]
	v_mov_b32_e32 v108, v140
	v_mov_b32_e32 v109, v138
	v_pk_mul_f32 v[134:135], v[104:105], v[104:105]
	v_pk_mul_f32 v[136:137], v[72:73], v[72:73]
	v_pk_add_f32 v[6:7], v[108:109], v[6:7]
	v_mov_b32_e32 v138, v141
	v_pk_add_f32 v[6:7], v[138:139], v[6:7]
	v_mov_b32_e32 v108, v136
	v_mov_b32_e32 v109, v134
	v_pk_mul_f32 v[130:131], v[102:103], v[102:103]
	v_pk_mul_f32 v[132:133], v[70:71], v[70:71]
	v_pk_add_f32 v[6:7], v[108:109], v[6:7]
	v_mov_b32_e32 v134, v137
	v_pk_add_f32 v[6:7], v[134:135], v[6:7]
	v_mov_b32_e32 v108, v132
	v_mov_b32_e32 v109, v130
	v_pk_add_f32 v[6:7], v[108:109], v[6:7]
	v_mov_b32_e32 v130, v133
	v_pk_add_f32 v[108:109], v[130:131], v[6:7]
	ds_bpermute_b32 v131, v184, v109
	ds_bpermute_b32 v130, v184, v108
	s_waitcnt vmcnt(0)
	v_mov_b32_e32 v6, v30
	v_mov_b32_e32 v7, v32
	v_mov_b32_e32 v32, v31
	s_mov_b32 s10, 0x3c800000
	s_waitcnt lgkmcnt(0)
	v_pk_add_f32 v[30:31], v[108:109], v[130:131]
	v_mov_b32_e32 v96, v50
	v_pk_fma_f32 v[30:31], v[30:31], s[10:11], v[174:175] op_sel_hi:[1,0,0]
	v_mov_b32_e32 v50, v42
	v_mul_f32_e32 v1, 0x4b800000, v31
	v_cmp_gt_f32_e32 vcc, s3, v31
	v_mov_b32_e32 v97, v52
	v_mov_b32_e32 v52, v51
	v_cndmask_b32_e32 v1, v31, v1, vcc
	v_rsq_f32_e32 v1, v1
	v_mov_b32_e32 v51, v44
	v_mov_b32_e32 v44, v43
	s_lshl_b64 s[10:11], s[18:19], 2
	v_mul_f32_e32 v31, 0x45800000, v1
	v_cndmask_b32_e32 v42, v1, v31, vcc
	v_pk_mul_f32 v[108:109], v[42:43], v[160:161] op_sel_hi:[0,1]
	v_pk_mul_f32 v[110:111], v[42:43], v[110:111] op_sel_hi:[0,1]
	v_pk_mul_f32 v[130:131], v[42:43], v[158:159] op_sel_hi:[0,1]
	v_pk_mul_f32 v[132:133], v[42:43], v[156:157] op_sel_hi:[0,1]
	v_pk_mul_f32 v[134:135], v[42:43], v[154:155] op_sel_hi:[0,1]
	v_pk_mul_f32 v[136:137], v[42:43], v[152:153] op_sel_hi:[0,1]
	v_pk_mul_f32 v[128:129], v[42:43], v[128:129] op_sel_hi:[0,1]
	v_pk_mul_f32 v[126:127], v[42:43], v[126:127] op_sel_hi:[0,1]
	v_pk_mul_f32 v[124:125], v[42:43], v[124:125] op_sel_hi:[0,1]
	v_pk_mul_f32 v[138:139], v[42:43], v[122:123] op_sel_hi:[0,1]
	v_pk_mul_f32 v[120:121], v[42:43], v[120:121] op_sel_hi:[0,1]
	v_pk_mul_f32 v[122:123], v[42:43], v[118:119] op_sel_hi:[0,1]
	v_pk_mul_f32 v[140:141], v[42:43], v[116:117] op_sel_hi:[0,1]
	v_pk_mul_f32 v[106:107], v[42:43], v[106:107] op_sel_hi:[0,1]
	v_pk_mul_f32 v[104:105], v[42:43], v[104:105] op_sel_hi:[0,1]
	v_pk_mul_f32 v[42:43], v[42:43], v[102:103] op_sel_hi:[0,1]
	v_pk_mul_f32 v[42:43], v[12:13], v[42:43]
	v_pk_mul_f32 v[102:103], v[60:61], v[132:133]
	v_pk_mul_f32 v[42:43], v[42:43], s[30:31] op_sel_hi:[1,0]
	v_mul_f32_e32 v1, 0x4b800000, v30
	v_cvt_pk_bf16_f32 v119, v42, v43
	v_pk_mul_f32 v[42:43], v[10:11], v[104:105]
	ds_bpermute_b32 v104, v184, v102
	v_pk_mul_f32 v[42:43], v[42:43], s[30:31] op_sel_hi:[1,0]
	ds_bpermute_b32 v105, v184, v103
	v_cvt_pk_bf16_f32 v118, v42, v43
	v_pk_mul_f32 v[42:43], v[16:17], v[106:107]
	v_cmp_gt_f32_e32 vcc, s3, v30
	v_pk_mul_f32 v[42:43], v[42:43], s[30:31] op_sel_hi:[1,0]
	s_add_u32 s10, s13, s10
	v_cvt_pk_bf16_f32 v117, v42, v43
	v_pk_mul_f32 v[42:43], v[14:15], v[140:141]
	v_cndmask_b32_e32 v1, v30, v1, vcc
	v_pk_mul_f32 v[42:43], v[42:43], s[30:31] op_sel_hi:[1,0]
	v_rsq_f32_e32 v1, v1
	v_cvt_pk_bf16_f32 v116, v42, v43
	v_pk_mul_f32 v[42:43], v[20:21], v[122:123]
	s_addc_u32 s11, s20, s11
	v_pk_mul_f32 v[42:43], v[42:43], s[30:31] op_sel_hi:[1,0]
	s_cmp_lg_u32 s24, 0
	v_cvt_pk_bf16_f32 v123, v42, v43
	v_pk_mul_f32 v[42:43], v[18:19], v[120:121]
	s_cselect_b64 s[14:15], -1, 0
	v_pk_mul_f32 v[42:43], v[42:43], s[30:31] op_sel_hi:[1,0]
	s_cmp_eq_u32 s24, 63
	v_cvt_pk_bf16_f32 v122, v42, v43
	v_pk_mul_f32 v[42:43], v[24:25], v[138:139]
	s_mov_b32 s3, 0
	v_pk_mul_f32 v[42:43], v[42:43], s[30:31] op_sel_hi:[1,0]
	v_mov_b32_e32 v198, v185
	v_cvt_pk_bf16_f32 v121, v42, v43
	v_pk_mul_f32 v[42:43], v[22:23], v[124:125]
	s_mov_b32 s24, 0
	v_pk_mul_f32 v[42:43], v[42:43], s[30:31] op_sel_hi:[1,0]
	s_nop 0
	v_cvt_pk_bf16_f32 v120, v42, v43
	v_pk_mul_f32 v[42:43], v[28:29], v[126:127]
	s_nop 0
	v_pk_mul_f32 v[42:43], v[42:43], s[30:31] op_sel_hi:[1,0]
	s_nop 0
	v_cvt_pk_bf16_f32 v127, v42, v43
	v_pk_mul_f32 v[42:43], v[26:27], v[128:129]
	s_nop 0
	v_pk_mul_f32 v[42:43], v[42:43], s[30:31] op_sel_hi:[1,0]
	s_nop 0
	v_cvt_pk_bf16_f32 v126, v42, v43
	v_pk_mul_f32 v[42:43], v[40:41], v[136:137]
	s_nop 0
	v_pk_mul_f32 v[42:43], v[42:43], s[30:31] op_sel_hi:[1,0]
	s_nop 0
	v_cvt_pk_bf16_f32 v125, v42, v43
	v_pk_mul_f32 v[42:43], v[38:39], v[134:135]
	s_nop 0
	v_pk_mul_f32 v[42:43], v[42:43], s[30:31] op_sel_hi:[1,0]
	s_nop 0
	v_cvt_pk_bf16_f32 v124, v42, v43
	s_waitcnt lgkmcnt(0)
	v_pk_mul_f32 v[42:43], v[48:49], v[104:105]
	v_pk_mul_f32 v[48:49], v[58:59], v[130:131]
	ds_bpermute_b32 v104, v184, v48
	ds_bpermute_b32 v105, v184, v49
	v_cndmask_b32_e64 v43, v43, -v43, s[42:43]
	v_cndmask_b32_e64 v42, v42, -v42, s[42:43]
	v_pk_fma_f32 v[42:43], v[102:103], v[98:99], v[42:43]
	s_nop 0
	v_pk_mul_f32 v[42:43], v[42:43], s[30:31] op_sel_hi:[1,0]
	s_nop 0
	v_cvt_pk_bf16_f32 v131, v42, v43
	s_waitcnt lgkmcnt(0)
	v_pk_mul_f32 v[42:43], v[56:57], v[104:105]
	v_pk_mul_f32 v[56:57], v[64:65], v[110:111]
	ds_bpermute_b32 v98, v184, v56
	ds_bpermute_b32 v99, v184, v57
	v_cndmask_b32_e64 v43, v43, -v43, s[42:43]
	v_cndmask_b32_e64 v42, v42, -v42, s[42:43]
	v_pk_fma_f32 v[42:43], v[48:49], v[100:101], v[42:43]
	v_pk_mul_f32 v[48:49], v[62:63], v[108:109]
	v_pk_mul_f32 v[42:43], v[42:43], s[30:31] op_sel_hi:[1,0]
	s_nop 0
	v_cvt_pk_bf16_f32 v130, v42, v43
	s_waitcnt lgkmcnt(0)
	v_pk_mul_f32 v[42:43], v[52:53], v[98:99]
	ds_bpermute_b32 v52, v184, v48
	ds_bpermute_b32 v53, v184, v49
	v_cndmask_b32_e64 v43, v43, -v43, s[42:43]
	v_cndmask_b32_e64 v42, v42, -v42, s[42:43]
	v_pk_fma_f32 v[42:43], v[96:97], v[56:57], v[42:43]
	s_nop 0
	v_pk_mul_f32 v[42:43], v[42:43], s[30:31] op_sel_hi:[1,0]
	s_nop 0
	v_cvt_pk_bf16_f32 v129, v42, v43
	s_waitcnt lgkmcnt(0)
	v_pk_mul_f32 v[42:43], v[44:45], v[52:53]
	s_nop 0
	v_cndmask_b32_e64 v43, v43, -v43, s[42:43]
	v_cndmask_b32_e64 v42, v42, -v42, s[42:43]
	v_pk_fma_f32 v[30:31], v[50:51], v[48:49], v[42:43]
	s_nop 0
	v_pk_mul_f32 v[30:31], v[30:31], s[30:31] op_sel_hi:[1,0]
	s_nop 0
	v_cvt_pk_bf16_f32 v128, v30, v31
	v_mul_f32_e32 v30, 0x45800000, v1
	v_cndmask_b32_e32 v30, v1, v30, vcc
	global_load_dword v1, v0, s[10:11]
	v_pk_mul_f32 v[52:53], v[30:31], v[92:93] op_sel_hi:[0,1]
	v_pk_mul_f32 v[38:39], v[38:39], v[52:53]
	v_pk_mul_f32 v[52:53], v[30:31], v[90:91] op_sel_hi:[0,1]
	v_pk_mul_f32 v[40:41], v[40:41], v[52:53]
	v_pk_mul_f32 v[52:53], v[30:31], v[88:89] op_sel_hi:[0,1]
	v_pk_mul_f32 v[26:27], v[26:27], v[52:53]
	v_pk_mul_f32 v[52:53], v[30:31], v[86:87] op_sel_hi:[0,1]
	v_pk_mul_f32 v[28:29], v[28:29], v[52:53]
	v_pk_mul_f32 v[52:53], v[30:31], v[84:85] op_sel_hi:[0,1]
	v_pk_mul_f32 v[22:23], v[22:23], v[52:53]
	v_pk_mul_f32 v[52:53], v[30:31], v[82:83] op_sel_hi:[0,1]
	v_pk_mul_f32 v[24:25], v[24:25], v[52:53]
	v_pk_mul_f32 v[52:53], v[30:31], v[80:81] op_sel_hi:[0,1]
	v_pk_mul_f32 v[18:19], v[18:19], v[52:53]
	v_pk_mul_f32 v[52:53], v[30:31], v[78:79] op_sel_hi:[0,1]
	v_pk_mul_f32 v[20:21], v[20:21], v[52:53]
	v_pk_mul_f32 v[52:53], v[30:31], v[76:77] op_sel_hi:[0,1]
	v_pk_mul_f32 v[44:45], v[30:31], v[68:69] op_sel_hi:[0,1]
	v_pk_mul_f32 v[14:15], v[14:15], v[52:53]
	v_pk_mul_f32 v[52:53], v[30:31], v[74:75] op_sel_hi:[0,1]
	v_pk_mul_f32 v[44:45], v[64:65], v[44:45]
	v_pk_mul_f32 v[16:17], v[16:17], v[52:53]
	v_pk_mul_f32 v[52:53], v[30:31], v[72:73] op_sel_hi:[0,1]
	v_pk_mul_f32 v[10:11], v[10:11], v[52:53]
	v_mov_b32_e32 v52, v34
	v_mov_b32_e32 v53, v36
	v_mov_b32_e32 v36, v35
	ds_bpermute_b32 v34, v184, v44
	ds_bpermute_b32 v35, v184, v45
	v_pk_mul_f32 v[48:49], v[30:31], v[54:55] op_sel_hi:[0,1]
	v_pk_mul_f32 v[48:49], v[58:59], v[48:49]
	v_pk_mul_f32 v[50:51], v[30:31], v[94:95] op_sel_hi:[0,1]
	v_pk_mul_f32 v[50:51], v[60:61], v[50:51]
	s_waitcnt lgkmcnt(0)
	v_pk_mul_f32 v[32:33], v[32:33], v[34:35]
	ds_bpermute_b32 v34, v184, v48
	v_cndmask_b32_e64 v33, v33, -v33, s[42:43]
	ds_bpermute_b32 v35, v184, v49
	v_cndmask_b32_e64 v32, v32, -v32, s[42:43]
	v_pk_fma_f32 v[6:7], v[6:7], v[44:45], v[32:33]
	ds_bpermute_b32 v32, v184, v50
	ds_bpermute_b32 v33, v184, v51
	s_waitcnt lgkmcnt(2)
	v_pk_mul_f32 v[8:9], v[8:9], v[34:35]
	v_pk_mul_f32 v[42:43], v[30:31], v[66:67] op_sel_hi:[0,1]
	v_cndmask_b32_e64 v9, v9, -v9, s[42:43]
	v_cndmask_b32_e64 v8, v8, -v8, s[42:43]
	s_waitcnt lgkmcnt(0)
	v_pk_mul_f32 v[4:5], v[4:5], v[32:33]
	v_pk_fma_f32 v[2:3], v[2:3], v[48:49], v[8:9]
	v_cndmask_b32_e64 v5, v5, -v5, s[42:43]
	v_cndmask_b32_e64 v4, v4, -v4, s[42:43]
	v_pk_fma_f32 v[4:5], v[46:47], v[50:51], v[4:5]
	v_pk_mul_f32 v[2:3], v[2:3], s[30:31] op_sel_hi:[1,0]
	v_pk_mul_f32 v[42:43], v[62:63], v[42:43]
	v_cvt_pk_bf16_f32 v134, v2, v3
	v_pk_mul_f32 v[2:3], v[4:5], s[30:31] op_sel_hi:[1,0]
	v_pk_mul_f32 v[30:31], v[30:31], v[70:71] op_sel_hi:[0,1]
	v_cvt_pk_bf16_f32 v135, v2, v3
	v_pk_mul_f32 v[2:3], v[38:39], s[30:31] op_sel_hi:[1,0]
	v_pk_mul_f32 v[12:13], v[12:13], v[30:31]
	v_cvt_pk_bf16_f32 v136, v2, v3
	v_pk_mul_f32 v[2:3], v[40:41], s[30:31] op_sel_hi:[1,0]
	ds_bpermute_b32 v30, v184, v42
	v_cvt_pk_bf16_f32 v137, v2, v3
	v_pk_mul_f32 v[2:3], v[26:27], s[30:31] op_sel_hi:[1,0]
	ds_bpermute_b32 v31, v184, v43
	v_cvt_pk_bf16_f32 v138, v2, v3
	v_pk_mul_f32 v[2:3], v[28:29], s[30:31] op_sel_hi:[1,0]
	v_pk_mul_f32 v[6:7], v[6:7], s[30:31] op_sel_hi:[1,0]
	v_cvt_pk_bf16_f32 v139, v2, v3
	v_pk_mul_f32 v[2:3], v[22:23], s[30:31] op_sel_hi:[1,0]
	s_waitcnt lgkmcnt(0)
	v_pk_mul_f32 v[30:31], v[36:37], v[30:31]
	v_cvt_pk_bf16_f32 v140, v2, v3
	v_pk_mul_f32 v[2:3], v[24:25], s[30:31] op_sel_hi:[1,0]
	v_cndmask_b32_e64 v31, v31, -v31, s[42:43]
	v_cvt_pk_bf16_f32 v141, v2, v3
	v_pk_mul_f32 v[2:3], v[18:19], s[30:31] op_sel_hi:[1,0]
	v_cndmask_b32_e64 v30, v30, -v30, s[42:43]
	v_cvt_pk_bf16_f32 v142, v2, v3
	v_pk_mul_f32 v[2:3], v[20:21], s[30:31] op_sel_hi:[1,0]
	v_pk_fma_f32 v[30:31], v[52:53], v[42:43], v[30:31]
	v_cvt_pk_bf16_f32 v143, v2, v3
	v_pk_mul_f32 v[2:3], v[14:15], s[30:31] op_sel_hi:[1,0]
	v_pk_mul_f32 v[8:9], v[30:31], s[30:31] op_sel_hi:[1,0]
	v_cvt_pk_bf16_f32 v144, v2, v3
	v_pk_mul_f32 v[2:3], v[16:17], s[30:31] op_sel_hi:[1,0]
	v_mov_b32_e32 v14, v0
	v_cvt_pk_bf16_f32 v145, v2, v3
	v_pk_mul_f32 v[2:3], v[10:11], s[30:31] op_sel_hi:[1,0]
	v_mov_b32_e32 v15, v0
	v_cvt_pk_bf16_f32 v146, v2, v3
	v_pk_mul_f32 v[2:3], v[12:13], s[30:31] op_sel_hi:[1,0]
	v_cvt_pk_bf16_f32 v132, v8, v9
	v_cvt_pk_bf16_f32 v133, v6, v7
	v_cvt_pk_bf16_f32 v147, v2, v3
	s_waitcnt vmcnt(0)
	v_mul_f32_e32 v199, 0x3fb8aa3b, v1
	s_movk_i32 s10, 0x180
	v_mov_b32_e32 v1, v0
	v_mov_b32_e32 v2, v0
	v_mov_b32_e32 v3, v0
	v_mov_b32_e32 v4, v0
	v_mov_b32_e32 v5, v0
	v_mov_b32_e32 v6, v0
	v_mov_b32_e32 v7, v0
	v_mov_b32_e32 v8, v0
	v_mov_b32_e32 v9, v0
	v_mov_b32_e32 v10, v0
	v_mov_b32_e32 v11, v0
	v_mov_b32_e32 v12, v0
	v_mov_b32_e32 v13, v0
	v_mov_b64_e32 v[30:31], v[14:15]
	v_mov_b64_e32 v[46:47], v[14:15]
	v_mov_b64_e32 v[62:63], v[14:15]
	v_mov_b64_e32 v[78:79], v[14:15]
	s_cselect_b32 s10, 0x100, s10
	s_mov_b32 s11, s22
	v_mov_b32_e32 v200, v199
	v_mov_b64_e32 v[28:29], v[12:13]
	v_mov_b64_e32 v[26:27], v[10:11]
	v_mov_b64_e32 v[24:25], v[8:9]
	v_mov_b64_e32 v[22:23], v[6:7]
	v_mov_b64_e32 v[20:21], v[4:5]
	v_mov_b64_e32 v[18:19], v[2:3]
	v_mov_b64_e32 v[16:17], v[0:1]
	v_mov_b64_e32 v[44:45], v[12:13]
	v_mov_b64_e32 v[42:43], v[10:11]
	v_mov_b64_e32 v[40:41], v[8:9]
	v_mov_b64_e32 v[38:39], v[6:7]
	v_mov_b64_e32 v[36:37], v[4:5]
	v_mov_b64_e32 v[34:35], v[2:3]
	v_mov_b64_e32 v[32:33], v[0:1]
	v_mov_b64_e32 v[60:61], v[12:13]
	v_mov_b64_e32 v[58:59], v[10:11]
	v_mov_b64_e32 v[56:57], v[8:9]
	v_mov_b64_e32 v[54:55], v[6:7]
	v_mov_b64_e32 v[52:53], v[4:5]
	v_mov_b64_e32 v[50:51], v[2:3]
	v_mov_b64_e32 v[48:49], v[0:1]
	v_mov_b64_e32 v[76:77], v[12:13]
	v_mov_b64_e32 v[74:75], v[10:11]
	v_mov_b64_e32 v[72:73], v[8:9]
	v_mov_b64_e32 v[70:71], v[6:7]
	v_mov_b64_e32 v[68:69], v[4:5]
	v_mov_b64_e32 v[66:67], v[2:3]
	v_mov_b64_e32 v[64:65], v[0:1]
	s_barrier
	s_branch .LBB0_360
